# resid epilogue rewritten (all x loads up front, stores after loads) + FFN weight conversion for later layers moved from phase 0 into idle SwiGLU tail workgroups
# speedup vs baseline: 1.0791x; 1.0791x over previous
.LBB0_33:
	s_add_u32 s0, s30, 0x100
	s_addc_u32 s1, s31, 0
	s_add_i32 s42, 0, 0x10000
	v_add_u32_e32 v96, s42, v229
	ds_read_b128 v[98:101], v96
	ds_read_b128 v[102:105], v96 offset:1024
	ds_read_b128 v[106:109], v96 offset:2048
	ds_read_b128 v[110:113], v96 offset:3072
	s_cmp_eq_u32 s52, 40
	s_cselect_b32 s47, s61, s1
	s_cselect_b32 s46, s60, s0
	s_cselect_b32 s45, s69, s51
	s_cselect_b32 s44, s68, s50
	v_lshl_add_u64 v[138:139], s[30:31], 0, v[146:147]
	s_add_i32 m0, s70, 0xc000
	ds_read_b128 v[114:117], v230
	ds_read_b128 v[118:121], v230 offset:1024
	ds_read_b128 v[122:125], v230 offset:2048
	ds_read_b128 v[126:129], v230 offset:3072
	ds_read_b128 v[130:133], v230 offset:4096
	ds_read_b128 v[134:137], v230 offset:5120
	global_load_lds_dwordx4 v[138:139], off
	v_lshl_add_u64 v[138:139], s[30:31], 0, v[148:149]
	s_add_i32 m0, s70, 0xe000
	s_nop 0
	global_load_lds_dwordx4 v[138:139], off
	s_waitcnt lgkmcnt(6)
	s_barrier
	s_waitcnt lgkmcnt(0)
	s_setprio 1
	s_waitcnt lgkmcnt(0)
	v_mfma_f32_16x16x32_bf16 v[92:95], v[98:101], v[114:117], v[92:95]
	v_mfma_f32_16x16x32_bf16 v[68:71], v[106:109], v[114:117], v[68:71]
	v_mfma_f32_16x16x32_bf16 v[88:91], v[98:101], v[122:125], v[88:91]
	v_mfma_f32_16x16x32_bf16 v[64:67], v[106:109], v[122:125], v[64:67]
	v_mfma_f32_16x16x32_bf16 v[84:87], v[98:101], v[130:133], v[84:87]
	v_mfma_f32_16x16x32_bf16 v[60:63], v[106:109], v[130:133], v[60:63]
	v_mfma_f32_16x16x32_bf16 v[92:95], v[102:105], v[118:121], v[92:95]
	v_mfma_f32_16x16x32_bf16 v[68:71], v[110:113], v[118:121], v[68:71]
	v_mfma_f32_16x16x32_bf16 v[88:91], v[102:105], v[126:129], v[88:91]
	v_mfma_f32_16x16x32_bf16 v[64:67], v[110:113], v[126:129], v[64:67]
	v_mfma_f32_16x16x32_bf16 v[84:87], v[102:105], v[134:137], v[84:87]
	v_mfma_f32_16x16x32_bf16 v[60:63], v[110:113], v[134:137], v[60:63]
	s_setprio 0
	s_barrier
	s_add_i32 s43, 0, 0x14000
	s_add_i32 s30, s42, s37
	v_add_u32_e32 v96, s43, v229
	v_lshl_add_u64 v[162:163], s[44:45], 0, v[144:145]
	s_mov_b32 m0, s30
	ds_read_b128 v[138:141], v96
	ds_read_b128 v[150:153], v96 offset:1024
	ds_read_b128 v[154:157], v96 offset:2048
	ds_read_b128 v[158:161], v96 offset:3072
	global_load_lds_dwordx4 v[162:163], off
	v_lshl_add_u64 v[164:165], s[44:45], 0, v[142:143]
	s_add_i32 m0, s30, 0x2000
	s_nop 0
	global_load_lds_dwordx4 v[164:165], off
	s_barrier
	s_waitcnt lgkmcnt(0)
	s_setprio 1
	s_waitcnt lgkmcnt(0)
	v_mfma_f32_16x16x32_bf16 v[48:51], v[138:141], v[114:117], v[48:51]
	v_mfma_f32_16x16x32_bf16 v[20:23], v[154:157], v[114:117], v[20:23]
	v_mfma_f32_16x16x32_bf16 v[40:43], v[138:141], v[122:125], v[40:43]
	v_mfma_f32_16x16x32_bf16 v[16:19], v[154:157], v[122:125], v[16:19]
	v_mfma_f32_16x16x32_bf16 v[36:39], v[138:141], v[130:133], v[36:39]
	v_mfma_f32_16x16x32_bf16 v[12:15], v[154:157], v[130:133], v[12:15]
	v_mfma_f32_16x16x32_bf16 v[48:51], v[150:153], v[118:121], v[48:51]
	v_mfma_f32_16x16x32_bf16 v[20:23], v[158:161], v[118:121], v[20:23]
	v_mfma_f32_16x16x32_bf16 v[40:43], v[150:153], v[126:129], v[40:43]
	v_mfma_f32_16x16x32_bf16 v[16:19], v[158:161], v[126:129], v[16:19]
	v_mfma_f32_16x16x32_bf16 v[36:39], v[150:153], v[134:137], v[36:39]
	v_mfma_f32_16x16x32_bf16 v[12:15], v[158:161], v[134:137], v[12:15]
	s_setprio 0
	s_mov_b32 m0, s70
	v_lshl_add_u64 v[166:167], s[46:47], 0, v[144:145]
	s_barrier
	ds_read_b128 v[114:117], v230 offset:16384
	ds_read_b128 v[118:121], v230 offset:17408
	ds_read_b128 v[122:125], v230 offset:18432
	ds_read_b128 v[126:129], v230 offset:19456
	ds_read_b128 v[130:133], v230 offset:20480
	ds_read_b128 v[134:137], v230 offset:21504
	global_load_lds_dwordx4 v[166:167], off
	v_lshl_add_u64 v[168:169], s[46:47], 0, v[142:143]
	s_mov_b32 m0, s71
	s_nop 0
	global_load_lds_dwordx4 v[168:169], off
	s_barrier
	s_waitcnt lgkmcnt(0)
	s_setprio 1
	s_waitcnt lgkmcnt(0)
	v_mfma_f32_16x16x32_bf16 v[80:83], v[98:101], v[114:117], v[80:83]
	v_mfma_f32_16x16x32_bf16 v[56:59], v[106:109], v[114:117], v[56:59]
	v_mfma_f32_16x16x32_bf16 v[76:79], v[98:101], v[122:125], v[76:79]
	v_mfma_f32_16x16x32_bf16 v[52:55], v[106:109], v[122:125], v[52:55]
	v_mfma_f32_16x16x32_bf16 v[72:75], v[98:101], v[130:133], v[72:75]
	v_mfma_f32_16x16x32_bf16 v[44:47], v[106:109], v[130:133], v[44:47]
	v_mfma_f32_16x16x32_bf16 v[80:83], v[102:105], v[118:121], v[80:83]
	v_mfma_f32_16x16x32_bf16 v[56:59], v[110:113], v[118:121], v[56:59]
	v_mfma_f32_16x16x32_bf16 v[76:79], v[102:105], v[126:129], v[76:79]
	v_mfma_f32_16x16x32_bf16 v[52:55], v[110:113], v[126:129], v[52:55]
	v_mfma_f32_16x16x32_bf16 v[72:75], v[102:105], v[134:137], v[72:75]
	v_mfma_f32_16x16x32_bf16 v[44:47], v[110:113], v[134:137], v[44:47]
	s_setprio 0
	s_barrier
	s_add_u32 s30, s44, 0xb0000
	s_addc_u32 s31, s45, 0
	s_add_i32 s42, s43, s37
	v_lshl_add_u64 v[98:99], s[30:31], 0, v[144:145]
	s_mov_b32 m0, s42
	s_nop 0
	global_load_lds_dwordx4 v[98:99], off
	v_lshl_add_u64 v[98:99], s[30:31], 0, v[142:143]
	s_add_i32 m0, s42, 0x2000
	s_nop 0
	global_load_lds_dwordx4 v[98:99], off
	s_waitcnt vmcnt(6)
	s_barrier
	s_setprio 1
	v_mfma_f32_16x16x32_bf16 v[32:35], v[138:141], v[114:117], v[32:35]
	v_mfma_f32_16x16x32_bf16 v[8:11], v[154:157], v[114:117], v[8:11]
	v_mfma_f32_16x16x32_bf16 v[28:31], v[138:141], v[122:125], v[28:31]
	v_mfma_f32_16x16x32_bf16 v[4:7], v[154:157], v[122:125], v[4:7]
	v_mfma_f32_16x16x32_bf16 v[24:27], v[138:141], v[130:133], v[24:27]
	v_mfma_f32_16x16x32_bf16 v[0:3], v[154:157], v[130:133], v[0:3]
	v_mfma_f32_16x16x32_bf16 v[32:35], v[150:153], v[118:121], v[32:35]
	v_mfma_f32_16x16x32_bf16 v[8:11], v[158:161], v[118:121], v[8:11]
	v_mfma_f32_16x16x32_bf16 v[28:31], v[150:153], v[126:129], v[28:31]
	v_mfma_f32_16x16x32_bf16 v[4:7], v[158:161], v[126:129], v[4:7]
	v_mfma_f32_16x16x32_bf16 v[24:27], v[150:153], v[134:137], v[24:27]
	v_mfma_f32_16x16x32_bf16 v[0:3], v[158:161], v[134:137], v[0:3]
	s_setprio 0
	s_add_i32 s42, 0, 0x18000
	v_add_u32_e32 v96, s42, v229
	s_barrier
	ds_read_b128 v[98:101], v96
	ds_read_b128 v[102:105], v96 offset:1024
	ds_read_b128 v[106:109], v96 offset:2048
	ds_read_b128 v[110:113], v96 offset:3072
	s_add_u32 s30, s46, 0x84000
	s_addc_u32 s31, s47, 0
	s_mov_b32 m0, s96
	v_lshl_add_u64 v[138:139], s[30:31], 0, v[144:145]
	ds_read_b128 v[114:117], v230 offset:32768
	ds_read_b128 v[118:121], v230 offset:33792
	ds_read_b128 v[122:125], v230 offset:34816
	ds_read_b128 v[126:129], v230 offset:35840
	ds_read_b128 v[130:133], v230 offset:36864
	ds_read_b128 v[134:137], v230 offset:37888
	global_load_lds_dwordx4 v[138:139], off
	v_lshl_add_u64 v[138:139], s[30:31], 0, v[142:143]
	s_mov_b32 m0, s97
	s_nop 0
	global_load_lds_dwordx4 v[138:139], off
	s_waitcnt lgkmcnt(6)
	s_barrier
	s_waitcnt lgkmcnt(0)
	s_setprio 1
	s_waitcnt lgkmcnt(0)
	v_mfma_f32_16x16x32_bf16 v[92:95], v[98:101], v[114:117], v[92:95]
	v_mfma_f32_16x16x32_bf16 v[68:71], v[106:109], v[114:117], v[68:71]
	v_mfma_f32_16x16x32_bf16 v[88:91], v[98:101], v[122:125], v[88:91]
	v_mfma_f32_16x16x32_bf16 v[64:67], v[106:109], v[122:125], v[64:67]
	v_mfma_f32_16x16x32_bf16 v[84:87], v[98:101], v[130:133], v[84:87]
	v_mfma_f32_16x16x32_bf16 v[60:63], v[106:109], v[130:133], v[60:63]
	v_mfma_f32_16x16x32_bf16 v[92:95], v[102:105], v[118:121], v[92:95]
	v_mfma_f32_16x16x32_bf16 v[68:71], v[110:113], v[118:121], v[68:71]
	v_mfma_f32_16x16x32_bf16 v[88:91], v[102:105], v[126:129], v[88:91]
	v_mfma_f32_16x16x32_bf16 v[64:67], v[110:113], v[126:129], v[64:67]
	v_mfma_f32_16x16x32_bf16 v[84:87], v[102:105], v[134:137], v[84:87]
	v_mfma_f32_16x16x32_bf16 v[60:63], v[110:113], v[134:137], v[60:63]
	s_setprio 0
	s_barrier
	s_add_i32 s43, 0, 0x1c000
	s_add_i32 s30, s42, s37
	v_add_u32_e32 v96, s43, v229
	v_lshl_add_u64 v[162:163], v[162:163], 0, s[56:57]
	s_mov_b32 m0, s30
	ds_read_b128 v[138:141], v96
	ds_read_b128 v[150:153], v96 offset:1024
	ds_read_b128 v[154:157], v96 offset:2048
	ds_read_b128 v[158:161], v96 offset:3072
	global_load_lds_dwordx4 v[162:163], off
	v_lshl_add_u64 v[162:163], v[164:165], 0, s[56:57]
	s_add_i32 m0, s30, 0x2000
	s_nop 0
	global_load_lds_dwordx4 v[162:163], off
	s_barrier
	s_waitcnt lgkmcnt(0)
	s_setprio 1
	s_waitcnt lgkmcnt(0)
	v_mfma_f32_16x16x32_bf16 v[48:51], v[138:141], v[114:117], v[48:51]
	v_mfma_f32_16x16x32_bf16 v[20:23], v[154:157], v[114:117], v[20:23]
	v_mfma_f32_16x16x32_bf16 v[40:43], v[138:141], v[122:125], v[40:43]
	v_mfma_f32_16x16x32_bf16 v[16:19], v[154:157], v[122:125], v[16:19]
	v_mfma_f32_16x16x32_bf16 v[36:39], v[138:141], v[130:133], v[36:39]
	v_mfma_f32_16x16x32_bf16 v[12:15], v[154:157], v[130:133], v[12:15]
	v_mfma_f32_16x16x32_bf16 v[48:51], v[150:153], v[118:121], v[48:51]
	v_mfma_f32_16x16x32_bf16 v[20:23], v[158:161], v[118:121], v[20:23]
	v_mfma_f32_16x16x32_bf16 v[40:43], v[150:153], v[126:129], v[40:43]
	v_mfma_f32_16x16x32_bf16 v[16:19], v[158:161], v[126:129], v[16:19]
	v_mfma_f32_16x16x32_bf16 v[36:39], v[150:153], v[134:137], v[36:39]
	v_mfma_f32_16x16x32_bf16 v[12:15], v[158:161], v[134:137], v[12:15]
	s_setprio 0
	s_mov_b32 m0, s24
	v_lshl_add_u64 v[162:163], v[166:167], 0, s[56:57]
	s_barrier
	ds_read_b128 v[114:117], v230 offset:49152
	ds_read_b128 v[118:121], v230 offset:50176
	ds_read_b128 v[122:125], v230 offset:51200
	ds_read_b128 v[126:129], v230 offset:52224
	ds_read_b128 v[130:133], v230 offset:53248
	ds_read_b128 v[134:137], v230 offset:54272
	global_load_lds_dwordx4 v[162:163], off
	v_lshl_add_u64 v[162:163], v[168:169], 0, s[56:57]
	s_mov_b32 m0, s36
	s_nop 0
	global_load_lds_dwordx4 v[162:163], off
	s_barrier
	s_waitcnt lgkmcnt(0)
	s_setprio 1
	s_waitcnt lgkmcnt(0)
	v_mfma_f32_16x16x32_bf16 v[80:83], v[98:101], v[114:117], v[80:83]
	v_mfma_f32_16x16x32_bf16 v[56:59], v[106:109], v[114:117], v[56:59]
	v_mfma_f32_16x16x32_bf16 v[76:79], v[98:101], v[122:125], v[76:79]
	v_mfma_f32_16x16x32_bf16 v[52:55], v[106:109], v[122:125], v[52:55]
	v_mfma_f32_16x16x32_bf16 v[72:75], v[98:101], v[130:133], v[72:75]
	v_mfma_f32_16x16x32_bf16 v[44:47], v[106:109], v[130:133], v[44:47]
	v_mfma_f32_16x16x32_bf16 v[80:83], v[102:105], v[118:121], v[80:83]
	v_mfma_f32_16x16x32_bf16 v[56:59], v[110:113], v[118:121], v[56:59]
	v_mfma_f32_16x16x32_bf16 v[76:79], v[102:105], v[126:129], v[76:79]
	v_mfma_f32_16x16x32_bf16 v[52:55], v[110:113], v[126:129], v[52:55]
	v_mfma_f32_16x16x32_bf16 v[72:75], v[102:105], v[134:137], v[72:75]
	v_mfma_f32_16x16x32_bf16 v[44:47], v[110:113], v[134:137], v[44:47]
	s_setprio 0
	s_barrier
	s_add_u32 s30, s44, 0xb0080
	s_addc_u32 s31, s45, 0
	s_add_i32 s42, s43, s37
	v_lshl_add_u64 v[98:99], s[30:31], 0, v[144:145]
	s_mov_b32 m0, s42
	s_nop 0
	global_load_lds_dwordx4 v[98:99], off
	v_lshl_add_u64 v[98:99], s[30:31], 0, v[142:143]
	s_add_i32 m0, s42, 0x2000
	s_nop 0
	global_load_lds_dwordx4 v[98:99], off
	s_waitcnt vmcnt(6)
	s_barrier
	s_setprio 1
	v_mfma_f32_16x16x32_bf16 v[32:35], v[138:141], v[114:117], v[32:35]
	v_mfma_f32_16x16x32_bf16 v[8:11], v[154:157], v[114:117], v[8:11]
	v_mfma_f32_16x16x32_bf16 v[28:31], v[138:141], v[122:125], v[28:31]
	v_mfma_f32_16x16x32_bf16 v[4:7], v[154:157], v[122:125], v[4:7]
	v_mfma_f32_16x16x32_bf16 v[24:27], v[138:141], v[130:133], v[24:27]
	v_mfma_f32_16x16x32_bf16 v[0:3], v[154:157], v[130:133], v[0:3]
	v_mfma_f32_16x16x32_bf16 v[32:35], v[150:153], v[118:121], v[32:35]
	v_mfma_f32_16x16x32_bf16 v[8:11], v[158:161], v[118:121], v[8:11]
	v_mfma_f32_16x16x32_bf16 v[28:31], v[150:153], v[126:129], v[28:31]
	v_mfma_f32_16x16x32_bf16 v[4:7], v[158:161], v[126:129], v[4:7]
	v_mfma_f32_16x16x32_bf16 v[24:27], v[150:153], v[134:137], v[24:27]
	v_mfma_f32_16x16x32_bf16 v[0:3], v[158:161], v[134:137], v[0:3]
	s_setprio 0
	s_add_i32 s52, s52, 2
	s_add_u32 s50, s50, 0x100
	s_addc_u32 s51, s51, 0
	s_cmp_gt_u32 s52, 41
	s_mov_b64 s[30:31], s[0:1]
	s_barrier
	s_cbranch_scc0 .LBB0_33
	s_mul_i32 s43, s48, 0xc0
	s_add_i32 s44, s43, s5
	v_add_u32_e32 v231, s44, v228
	s_lshl_b32 s44, s49, 8
	s_or_b32 s44, s44, s4
	v_lshl_add_u32 v233, v171, 2, s44
	s_add_i32 s44, s43, 0xffffe000
	s_ashr_i32 s45, s44, 11
	s_add_i32 s45, s45, 1
	s_max_i32 s45, s45, 0
	s_addk_i32 s44, 0xbf
	s_ashr_i32 s44, s44, 11
	s_add_i32 s44, s44, 1
	s_max_i32 s44, s44, 0
	s_lshl_b32 s46, s45, 11
	s_addk_i32 s46, 0x2000
	s_lshl_b32 s46, s46, 12
	s_cmp_lg_u32 s44, s45
	s_cselect_b32 s42, s46, -1
	s_cselect_b32 s47, 0x9000, 0
	s_mul_i32 s45, s45, 0x9000
	s_add_u32 s0, s58, s45
	s_addc_u32 s1, s59, 0
	s_add_u32 s30, s0, s47
	s_addc_u32 s31, s1, 0
	v_lshlrev_b32_e32 v96, 2, v233
	v_lshl_add_u32 v206, v231, 12, v96
	v_add_u32_e32 v207, 0x10000, v206
	v_add_u32_e32 v208, 0x20000, v206
	v_add_u32_e32 v209, 0x60000, v206
	v_add_u32_e32 v216, 0x70000, v206
	v_add_u32_e32 v217, 0x80000, v206
	global_load_dwordx4 v[184:187], v96, s[0:1] offset:0
	global_load_dwordx4 v[188:191], v96, s[30:31] offset:0
	global_load_dwordx4 v[98:101], v206, s[90:91] offset:0
	global_load_dwordx4 v[102:105], v207, s[90:91] offset:0
	global_load_dwordx4 v[106:109], v208, s[90:91] offset:0
	global_load_dwordx4 v[110:113], v209, s[90:91] offset:0
	global_load_dwordx4 v[114:117], v216, s[90:91] offset:0
	global_load_dwordx4 v[118:121], v217, s[90:91] offset:0
	global_load_dwordx4 v[192:195], v96, s[0:1] offset:64
	global_load_dwordx4 v[196:199], v96, s[30:31] offset:64
	global_load_dwordx4 v[122:125], v206, s[90:91] offset:64
	global_load_dwordx4 v[126:129], v207, s[90:91] offset:64
	global_load_dwordx4 v[130:133], v208, s[90:91] offset:64
	global_load_dwordx4 v[134:137], v209, s[90:91] offset:64
	global_load_dwordx4 v[150:153], v216, s[90:91] offset:64
	global_load_dwordx4 v[154:157], v217, s[90:91] offset:64
	global_load_dwordx4 v[158:161], v206, s[90:91] offset:512
	global_load_dwordx4 v[162:165], v207, s[90:91] offset:512
	global_load_dwordx4 v[166:169], v208, s[90:91] offset:512
	global_load_dwordx4 v[172:175], v209, s[90:91] offset:512
	global_load_dwordx4 v[176:179], v216, s[90:91] offset:512
	global_load_dwordx4 v[180:183], v217, s[90:91] offset:512
	v_cmp_le_u32_e64 s[44:45], s42, v206
	v_cmp_le_u32_e64 s[46:47], s42, v207
	v_cmp_le_u32_e64 s[48:49], s42, v208
	v_cmp_le_u32_e64 s[50:51], s42, v209
	v_cmp_le_u32_e64 s[52:53], s42, v216
	v_cmp_le_u32_e32 vcc, s42, v217
	s_waitcnt vmcnt(14)
	v_pk_mul_f32 v[184:185], v[184:185], 0.5 op_sel_hi:[1,0]
	v_pk_mul_f32 v[186:187], v[186:187], 0.5 op_sel_hi:[1,0]
	v_pk_mul_f32 v[188:189], v[188:189], 0.5 op_sel_hi:[1,0]
	v_pk_mul_f32 v[190:191], v[190:191], 0.5 op_sel_hi:[1,0]
	v_cndmask_b32_e64 v242, v184, v188, s[44:45]
	v_cndmask_b32_e64 v243, v185, v189, s[44:45]
	v_cndmask_b32_e64 v244, v186, v190, s[44:45]
	v_cndmask_b32_e64 v245, v187, v191, s[44:45]
	v_pk_fma_f32 v[92:93], v[92:93], v[242:243], v[98:99]
	v_pk_fma_f32 v[94:95], v[94:95], v[244:245], v[100:101]
	v_cndmask_b32_e64 v242, v184, v188, s[46:47]
	v_cndmask_b32_e64 v243, v185, v189, s[46:47]
	v_cndmask_b32_e64 v244, v186, v190, s[46:47]
	v_cndmask_b32_e64 v245, v187, v191, s[46:47]
	v_pk_fma_f32 v[88:89], v[88:89], v[242:243], v[102:103]
	v_pk_fma_f32 v[90:91], v[90:91], v[244:245], v[104:105]
	v_cndmask_b32_e64 v242, v184, v188, s[48:49]
	v_cndmask_b32_e64 v243, v185, v189, s[48:49]
	v_cndmask_b32_e64 v244, v186, v190, s[48:49]
	v_cndmask_b32_e64 v245, v187, v191, s[48:49]
	v_pk_fma_f32 v[84:85], v[84:85], v[242:243], v[106:107]
	v_pk_fma_f32 v[86:87], v[86:87], v[244:245], v[108:109]
	v_cndmask_b32_e64 v242, v184, v188, s[50:51]
	v_cndmask_b32_e64 v243, v185, v189, s[50:51]
	v_cndmask_b32_e64 v244, v186, v190, s[50:51]
	v_cndmask_b32_e64 v245, v187, v191, s[50:51]
	v_pk_fma_f32 v[80:81], v[80:81], v[242:243], v[110:111]
	v_pk_fma_f32 v[82:83], v[82:83], v[244:245], v[112:113]
	v_cndmask_b32_e64 v242, v184, v188, s[52:53]
	v_cndmask_b32_e64 v243, v185, v189, s[52:53]
	v_cndmask_b32_e64 v244, v186, v190, s[52:53]
	v_cndmask_b32_e64 v245, v187, v191, s[52:53]
	v_pk_fma_f32 v[76:77], v[76:77], v[242:243], v[114:115]
	v_pk_fma_f32 v[78:79], v[78:79], v[244:245], v[116:117]
	v_cndmask_b32_e32 v242, v184, v188, vcc
	v_cndmask_b32_e32 v243, v185, v189, vcc
	v_cndmask_b32_e32 v244, v186, v190, vcc
	v_cndmask_b32_e32 v245, v187, v191, vcc
	v_pk_fma_f32 v[72:73], v[72:73], v[242:243], v[118:119]
	v_pk_fma_f32 v[74:75], v[74:75], v[244:245], v[120:121]
	global_load_dwordx4 v[98:101], v206, s[90:91] offset:576
	global_load_dwordx4 v[102:105], v207, s[90:91] offset:576
	global_load_dwordx4 v[106:109], v208, s[90:91] offset:576
	global_load_dwordx4 v[110:113], v209, s[90:91] offset:576
	global_load_dwordx4 v[114:117], v216, s[90:91] offset:576
	global_load_dwordx4 v[118:121], v217, s[90:91] offset:576
	global_load_dwordx4 v[184:187], v96, s[0:1] offset:512
	global_load_dwordx4 v[188:191], v96, s[30:31] offset:512
	global_load_dwordx4 v[234:237], v96, s[0:1] offset:576
	global_load_dwordx4 v[238:241], v96, s[30:31] offset:576
	s_waitcnt vmcnt(16)
	v_pk_mul_f32 v[192:193], v[192:193], 0.5 op_sel_hi:[1,0]
	v_pk_mul_f32 v[194:195], v[194:195], 0.5 op_sel_hi:[1,0]
	v_pk_mul_f32 v[196:197], v[196:197], 0.5 op_sel_hi:[1,0]
	v_pk_mul_f32 v[198:199], v[198:199], 0.5 op_sel_hi:[1,0]
	v_cndmask_b32_e64 v242, v192, v196, s[44:45]
	v_cndmask_b32_e64 v243, v193, v197, s[44:45]
	v_cndmask_b32_e64 v244, v194, v198, s[44:45]
	v_cndmask_b32_e64 v245, v195, v199, s[44:45]
	v_pk_fma_f32 v[68:69], v[68:69], v[242:243], v[122:123]
	v_pk_fma_f32 v[70:71], v[70:71], v[244:245], v[124:125]
	v_cndmask_b32_e64 v242, v192, v196, s[46:47]
	v_cndmask_b32_e64 v243, v193, v197, s[46:47]
	v_cndmask_b32_e64 v244, v194, v198, s[46:47]
	v_cndmask_b32_e64 v245, v195, v199, s[46:47]
	v_pk_fma_f32 v[64:65], v[64:65], v[242:243], v[126:127]
	v_pk_fma_f32 v[66:67], v[66:67], v[244:245], v[128:129]
	v_cndmask_b32_e64 v242, v192, v196, s[48:49]
	v_cndmask_b32_e64 v243, v193, v197, s[48:49]
	v_cndmask_b32_e64 v244, v194, v198, s[48:49]
	v_cndmask_b32_e64 v245, v195, v199, s[48:49]
	v_pk_fma_f32 v[60:61], v[60:61], v[242:243], v[130:131]
	v_pk_fma_f32 v[62:63], v[62:63], v[244:245], v[132:133]
	v_cndmask_b32_e64 v242, v192, v196, s[50:51]
	v_cndmask_b32_e64 v243, v193, v197, s[50:51]
	v_cndmask_b32_e64 v244, v194, v198, s[50:51]
	v_cndmask_b32_e64 v245, v195, v199, s[50:51]
	v_pk_fma_f32 v[56:57], v[56:57], v[242:243], v[134:135]
	v_pk_fma_f32 v[58:59], v[58:59], v[244:245], v[136:137]
	v_cndmask_b32_e64 v242, v192, v196, s[52:53]
	v_cndmask_b32_e64 v243, v193, v197, s[52:53]
	v_cndmask_b32_e64 v244, v194, v198, s[52:53]
	v_cndmask_b32_e64 v245, v195, v199, s[52:53]
	v_pk_fma_f32 v[52:53], v[52:53], v[242:243], v[150:151]
	v_pk_fma_f32 v[54:55], v[54:55], v[244:245], v[152:153]
	v_cndmask_b32_e32 v242, v192, v196, vcc
	v_cndmask_b32_e32 v243, v193, v197, vcc
	v_cndmask_b32_e32 v244, v194, v198, vcc
	v_cndmask_b32_e32 v245, v195, v199, vcc
	v_pk_fma_f32 v[44:45], v[44:45], v[242:243], v[154:155]
	v_pk_fma_f32 v[46:47], v[46:47], v[244:245], v[156:157]
	s_waitcnt vmcnt(0)
	v_pk_mul_f32 v[184:185], v[184:185], 0.5 op_sel_hi:[1,0]
	v_pk_mul_f32 v[186:187], v[186:187], 0.5 op_sel_hi:[1,0]
	v_pk_mul_f32 v[188:189], v[188:189], 0.5 op_sel_hi:[1,0]
	v_pk_mul_f32 v[190:191], v[190:191], 0.5 op_sel_hi:[1,0]
	v_cndmask_b32_e64 v242, v184, v188, s[44:45]
	v_cndmask_b32_e64 v243, v185, v189, s[44:45]
	v_cndmask_b32_e64 v244, v186, v190, s[44:45]
	v_cndmask_b32_e64 v245, v187, v191, s[44:45]
	v_pk_fma_f32 v[48:49], v[48:49], v[242:243], v[158:159]
	v_pk_fma_f32 v[50:51], v[50:51], v[244:245], v[160:161]
	v_cndmask_b32_e64 v242, v184, v188, s[46:47]
	v_cndmask_b32_e64 v243, v185, v189, s[46:47]
	v_cndmask_b32_e64 v244, v186, v190, s[46:47]
	v_cndmask_b32_e64 v245, v187, v191, s[46:47]
	v_pk_fma_f32 v[40:41], v[40:41], v[242:243], v[162:163]
	v_pk_fma_f32 v[42:43], v[42:43], v[244:245], v[164:165]
	v_cndmask_b32_e64 v242, v184, v188, s[48:49]
	v_cndmask_b32_e64 v243, v185, v189, s[48:49]
	v_cndmask_b32_e64 v244, v186, v190, s[48:49]
	v_cndmask_b32_e64 v245, v187, v191, s[48:49]
	v_pk_fma_f32 v[36:37], v[36:37], v[242:243], v[166:167]
	v_pk_fma_f32 v[38:39], v[38:39], v[244:245], v[168:169]
	v_cndmask_b32_e64 v242, v184, v188, s[50:51]
	v_cndmask_b32_e64 v243, v185, v189, s[50:51]
	v_cndmask_b32_e64 v244, v186, v190, s[50:51]
	v_cndmask_b32_e64 v245, v187, v191, s[50:51]
	v_pk_fma_f32 v[32:33], v[32:33], v[242:243], v[172:173]
	v_pk_fma_f32 v[34:35], v[34:35], v[244:245], v[174:175]
	v_cndmask_b32_e64 v242, v184, v188, s[52:53]
	v_cndmask_b32_e64 v243, v185, v189, s[52:53]
	v_cndmask_b32_e64 v244, v186, v190, s[52:53]
	v_cndmask_b32_e64 v245, v187, v191, s[52:53]
	v_pk_fma_f32 v[28:29], v[28:29], v[242:243], v[176:177]
	v_pk_fma_f32 v[30:31], v[30:31], v[244:245], v[178:179]
	v_cndmask_b32_e32 v242, v184, v188, vcc
	v_cndmask_b32_e32 v243, v185, v189, vcc
	v_cndmask_b32_e32 v244, v186, v190, vcc
	v_cndmask_b32_e32 v245, v187, v191, vcc
	v_pk_fma_f32 v[24:25], v[24:25], v[242:243], v[180:181]
	v_pk_fma_f32 v[26:27], v[26:27], v[244:245], v[182:183]
	v_pk_mul_f32 v[234:235], v[234:235], 0.5 op_sel_hi:[1,0]
	v_pk_mul_f32 v[236:237], v[236:237], 0.5 op_sel_hi:[1,0]
	v_pk_mul_f32 v[238:239], v[238:239], 0.5 op_sel_hi:[1,0]
	v_pk_mul_f32 v[240:241], v[240:241], 0.5 op_sel_hi:[1,0]
	v_cndmask_b32_e64 v242, v234, v238, s[44:45]
	v_cndmask_b32_e64 v243, v235, v239, s[44:45]
	v_cndmask_b32_e64 v244, v236, v240, s[44:45]
	v_cndmask_b32_e64 v245, v237, v241, s[44:45]
	v_pk_fma_f32 v[20:21], v[20:21], v[242:243], v[98:99]
	v_pk_fma_f32 v[22:23], v[22:23], v[244:245], v[100:101]
	v_cndmask_b32_e64 v242, v234, v238, s[46:47]
	v_cndmask_b32_e64 v243, v235, v239, s[46:47]
	v_cndmask_b32_e64 v244, v236, v240, s[46:47]
	v_cndmask_b32_e64 v245, v237, v241, s[46:47]
	v_pk_fma_f32 v[16:17], v[16:17], v[242:243], v[102:103]
	v_pk_fma_f32 v[18:19], v[18:19], v[244:245], v[104:105]
	v_cndmask_b32_e64 v242, v234, v238, s[48:49]
	v_cndmask_b32_e64 v243, v235, v239, s[48:49]
	v_cndmask_b32_e64 v244, v236, v240, s[48:49]
	v_cndmask_b32_e64 v245, v237, v241, s[48:49]
	v_pk_fma_f32 v[12:13], v[12:13], v[242:243], v[106:107]
	v_pk_fma_f32 v[14:15], v[14:15], v[244:245], v[108:109]
	v_cndmask_b32_e64 v242, v234, v238, s[50:51]
	v_cndmask_b32_e64 v243, v235, v239, s[50:51]
	v_cndmask_b32_e64 v244, v236, v240, s[50:51]
	v_cndmask_b32_e64 v245, v237, v241, s[50:51]
	v_pk_fma_f32 v[8:9], v[8:9], v[242:243], v[110:111]
	v_pk_fma_f32 v[10:11], v[10:11], v[244:245], v[112:113]
	v_cndmask_b32_e64 v242, v234, v238, s[52:53]
	v_cndmask_b32_e64 v243, v235, v239, s[52:53]
	v_cndmask_b32_e64 v244, v236, v240, s[52:53]
	v_cndmask_b32_e64 v245, v237, v241, s[52:53]
	v_pk_fma_f32 v[4:5], v[4:5], v[242:243], v[114:115]
	v_pk_fma_f32 v[6:7], v[6:7], v[244:245], v[116:117]
	v_cndmask_b32_e32 v242, v234, v238, vcc
	v_cndmask_b32_e32 v243, v235, v239, vcc
	v_cndmask_b32_e32 v244, v236, v240, vcc
	v_cndmask_b32_e32 v245, v237, v241, vcc
	v_pk_fma_f32 v[0:1], v[0:1], v[242:243], v[118:119]
	v_pk_fma_f32 v[2:3], v[2:3], v[244:245], v[120:121]
	global_store_dwordx4 v206, v[92:95], s[90:91] offset:0
	global_store_dwordx4 v207, v[88:91], s[90:91] offset:0
	global_store_dwordx4 v208, v[84:87], s[90:91] offset:0
	global_store_dwordx4 v209, v[80:83], s[90:91] offset:0
	global_store_dwordx4 v216, v[76:79], s[90:91] offset:0
	global_store_dwordx4 v217, v[72:75], s[90:91] offset:0
	global_store_dwordx4 v206, v[68:71], s[90:91] offset:64
	global_store_dwordx4 v207, v[64:67], s[90:91] offset:64
	global_store_dwordx4 v208, v[60:63], s[90:91] offset:64
	global_store_dwordx4 v209, v[56:59], s[90:91] offset:64
	global_store_dwordx4 v216, v[52:55], s[90:91] offset:64
	global_store_dwordx4 v217, v[44:47], s[90:91] offset:64
	global_store_dwordx4 v206, v[48:51], s[90:91] offset:512
	global_store_dwordx4 v207, v[40:43], s[90:91] offset:512
	global_store_dwordx4 v208, v[36:39], s[90:91] offset:512
	global_store_dwordx4 v209, v[32:35], s[90:91] offset:512
	global_store_dwordx4 v216, v[28:31], s[90:91] offset:512
	global_store_dwordx4 v217, v[24:27], s[90:91] offset:512
	global_store_dwordx4 v206, v[20:23], s[90:91] offset:576
	global_store_dwordx4 v207, v[16:19], s[90:91] offset:576
	global_store_dwordx4 v208, v[12:15], s[90:91] offset:576
	global_store_dwordx4 v209, v[8:11], s[90:91] offset:576
	global_store_dwordx4 v216, v[4:7], s[90:91] offset:576
	global_store_dwordx4 v217, v[0:3], s[90:91] offset:576
	s_branch .LBB0_21

.LBB0_78:
	v_readlane_b32 s80, v255, 42
	v_readlane_b32 s84, v255, 44
	v_readlane_b32 s81, v255, 43
	v_readlane_b32 s85, v255, 45
	v_readlane_b32 s77, v255, 46
	v_readlane_b32 s76, v255, 47
	s_barrier
	s_cmp_lt_u32 s34, 64
	s_cbranch_scc1 .Lp0t_done_q10
	v_readlane_b32 s0, v255, 48
	s_cmp_eq_u32 s0, 11
	s_cbranch_scc0 .Lp0t_n0_q10
	s_sub_i32 s32, s34, 64
	s_addk_i32 s32, 0x660
	s_movk_i32 s69, 0x86f
	s_cmp_gt_i32 s32, s69
	s_cbranch_scc1 .Lp0t_done_q10
	s_movk_i32 s68, 0xc0
	s_mov_b32 s70, 0
	s_mov_b32 s71, 0
	v_mov_b32_e32 v0, v204
	s_branch .Lp0_tramp
.Lp0t_n0_q10:
.Lp0t_done_q10:
.LBB0_79:
	s_mov_b64 s[0:1], 0

.LBB0_107:
	s_add_u32 s0, s30, 0x100
	s_addc_u32 s1, s31, 0
	s_add_i32 s42, 0, 0x10000
	v_add_u32_e32 v96, s42, v203
	ds_read_b128 v[98:101], v96
	ds_read_b128 v[102:105], v96 offset:1024
	ds_read_b128 v[106:109], v96 offset:2048
	ds_read_b128 v[110:113], v96 offset:3072
	s_cmp_eq_u32 s61, 12
	s_cselect_b32 s47, s69, s1
	s_cselect_b32 s46, s68, s0
	s_cselect_b32 s45, s50, s53
	s_cselect_b32 s44, s51, s52
	v_lshl_add_u64 v[146:147], s[30:31], 0, v[142:143]
	s_add_i32 m0, s72, 0xc000
	ds_read_b128 v[114:117], v228
	ds_read_b128 v[118:121], v228 offset:1024
	ds_read_b128 v[122:125], v228 offset:2048
	ds_read_b128 v[126:129], v228 offset:3072
	ds_read_b128 v[130:133], v228 offset:4096
	ds_read_b128 v[134:137], v228 offset:5120
	global_load_lds_dwordx4 v[146:147], off
	v_lshl_add_u64 v[146:147], s[30:31], 0, v[144:145]
	s_add_i32 m0, s72, 0xe000
	s_nop 0
	global_load_lds_dwordx4 v[146:147], off
	s_waitcnt lgkmcnt(6)
	s_barrier
	s_waitcnt lgkmcnt(0)
	s_setprio 1
	s_waitcnt lgkmcnt(0)
	v_mfma_f32_16x16x32_bf16 v[92:95], v[98:101], v[114:117], v[92:95]
	v_mfma_f32_16x16x32_bf16 v[68:71], v[106:109], v[114:117], v[68:71]
	v_mfma_f32_16x16x32_bf16 v[88:91], v[98:101], v[122:125], v[88:91]
	v_mfma_f32_16x16x32_bf16 v[64:67], v[106:109], v[122:125], v[64:67]
	v_mfma_f32_16x16x32_bf16 v[84:87], v[98:101], v[130:133], v[84:87]
	v_mfma_f32_16x16x32_bf16 v[60:63], v[106:109], v[130:133], v[60:63]
	v_mfma_f32_16x16x32_bf16 v[92:95], v[102:105], v[118:121], v[92:95]
	v_mfma_f32_16x16x32_bf16 v[68:71], v[110:113], v[118:121], v[68:71]
	v_mfma_f32_16x16x32_bf16 v[88:91], v[102:105], v[126:129], v[88:91]
	v_mfma_f32_16x16x32_bf16 v[64:67], v[110:113], v[126:129], v[64:67]
	v_mfma_f32_16x16x32_bf16 v[84:87], v[102:105], v[134:137], v[84:87]
	v_mfma_f32_16x16x32_bf16 v[60:63], v[110:113], v[134:137], v[60:63]
	s_setprio 0
	s_barrier
	s_add_i32 s43, 0, 0x14000
	s_add_i32 s30, s42, s37
	v_add_u32_e32 v96, s43, v203
	v_lshl_add_u64 v[162:163], s[44:45], 0, v[140:141]
	s_mov_b32 m0, s30
	ds_read_b128 v[146:149], v96
	ds_read_b128 v[150:153], v96 offset:1024
	ds_read_b128 v[154:157], v96 offset:2048
	ds_read_b128 v[158:161], v96 offset:3072
	global_load_lds_dwordx4 v[162:163], off
	v_lshl_add_u64 v[164:165], s[44:45], 0, v[138:139]
	s_add_i32 m0, s30, 0x2000
	s_nop 0
	global_load_lds_dwordx4 v[164:165], off
	s_barrier
	s_waitcnt lgkmcnt(0)
	s_setprio 1
	s_waitcnt lgkmcnt(0)
	v_mfma_f32_16x16x32_bf16 v[44:47], v[146:149], v[114:117], v[44:47]
	v_mfma_f32_16x16x32_bf16 v[20:23], v[154:157], v[114:117], v[20:23]
	v_mfma_f32_16x16x32_bf16 v[40:43], v[146:149], v[122:125], v[40:43]
	v_mfma_f32_16x16x32_bf16 v[16:19], v[154:157], v[122:125], v[16:19]
	v_mfma_f32_16x16x32_bf16 v[36:39], v[146:149], v[130:133], v[36:39]
	v_mfma_f32_16x16x32_bf16 v[12:15], v[154:157], v[130:133], v[12:15]
	v_mfma_f32_16x16x32_bf16 v[44:47], v[150:153], v[118:121], v[44:47]
	v_mfma_f32_16x16x32_bf16 v[20:23], v[158:161], v[118:121], v[20:23]
	v_mfma_f32_16x16x32_bf16 v[40:43], v[150:153], v[126:129], v[40:43]
	v_mfma_f32_16x16x32_bf16 v[16:19], v[158:161], v[126:129], v[16:19]
	v_mfma_f32_16x16x32_bf16 v[36:39], v[150:153], v[134:137], v[36:39]
	v_mfma_f32_16x16x32_bf16 v[12:15], v[158:161], v[134:137], v[12:15]
	s_setprio 0
	s_mov_b32 m0, s72
	v_lshl_add_u64 v[166:167], s[46:47], 0, v[140:141]
	s_barrier
	ds_read_b128 v[114:117], v228 offset:16384
	ds_read_b128 v[118:121], v228 offset:17408
	ds_read_b128 v[122:125], v228 offset:18432
	ds_read_b128 v[126:129], v228 offset:19456
	ds_read_b128 v[130:133], v228 offset:20480
	ds_read_b128 v[134:137], v228 offset:21504
	global_load_lds_dwordx4 v[166:167], off
	v_lshl_add_u64 v[168:169], s[46:47], 0, v[138:139]
	s_mov_b32 m0, s73
	s_nop 0
	global_load_lds_dwordx4 v[168:169], off
	s_barrier
	s_waitcnt lgkmcnt(0)
	s_setprio 1
	s_waitcnt lgkmcnt(0)
	v_mfma_f32_16x16x32_bf16 v[80:83], v[98:101], v[114:117], v[80:83]
	v_mfma_f32_16x16x32_bf16 v[56:59], v[106:109], v[114:117], v[56:59]
	v_mfma_f32_16x16x32_bf16 v[76:79], v[98:101], v[122:125], v[76:79]
	v_mfma_f32_16x16x32_bf16 v[52:55], v[106:109], v[122:125], v[52:55]
	v_mfma_f32_16x16x32_bf16 v[72:75], v[98:101], v[130:133], v[72:75]
	v_mfma_f32_16x16x32_bf16 v[48:51], v[106:109], v[130:133], v[48:51]
	v_mfma_f32_16x16x32_bf16 v[80:83], v[102:105], v[118:121], v[80:83]
	v_mfma_f32_16x16x32_bf16 v[56:59], v[110:113], v[118:121], v[56:59]
	v_mfma_f32_16x16x32_bf16 v[76:79], v[102:105], v[126:129], v[76:79]
	v_mfma_f32_16x16x32_bf16 v[52:55], v[110:113], v[126:129], v[52:55]
	v_mfma_f32_16x16x32_bf16 v[72:75], v[102:105], v[134:137], v[72:75]
	v_mfma_f32_16x16x32_bf16 v[48:51], v[110:113], v[134:137], v[48:51]
	s_setprio 0
	s_barrier
	s_add_u32 s30, s44, 0x40000
	s_addc_u32 s31, s45, 0
	s_add_i32 s42, s43, s37
	v_lshl_add_u64 v[98:99], s[30:31], 0, v[140:141]
	s_mov_b32 m0, s42
	s_nop 0
	global_load_lds_dwordx4 v[98:99], off
	v_lshl_add_u64 v[98:99], s[30:31], 0, v[138:139]
	s_add_i32 m0, s42, 0x2000
	s_nop 0
	global_load_lds_dwordx4 v[98:99], off
	s_waitcnt vmcnt(6)
	s_barrier
	s_setprio 1
	v_mfma_f32_16x16x32_bf16 v[32:35], v[146:149], v[114:117], v[32:35]
	v_mfma_f32_16x16x32_bf16 v[8:11], v[154:157], v[114:117], v[8:11]
	v_mfma_f32_16x16x32_bf16 v[28:31], v[146:149], v[122:125], v[28:31]
	v_mfma_f32_16x16x32_bf16 v[4:7], v[154:157], v[122:125], v[4:7]
	v_mfma_f32_16x16x32_bf16 v[24:27], v[146:149], v[130:133], v[24:27]
	v_mfma_f32_16x16x32_bf16 v[0:3], v[154:157], v[130:133], v[0:3]
	v_mfma_f32_16x16x32_bf16 v[32:35], v[150:153], v[118:121], v[32:35]
	v_mfma_f32_16x16x32_bf16 v[8:11], v[158:161], v[118:121], v[8:11]
	v_mfma_f32_16x16x32_bf16 v[28:31], v[150:153], v[126:129], v[28:31]
	v_mfma_f32_16x16x32_bf16 v[4:7], v[158:161], v[126:129], v[4:7]
	v_mfma_f32_16x16x32_bf16 v[24:27], v[150:153], v[134:137], v[24:27]
	v_mfma_f32_16x16x32_bf16 v[0:3], v[158:161], v[134:137], v[0:3]
	s_setprio 0
	s_add_i32 s42, 0, 0x18000
	v_add_u32_e32 v96, s42, v203
	s_barrier
	ds_read_b128 v[98:101], v96
	ds_read_b128 v[102:105], v96 offset:1024
	ds_read_b128 v[106:109], v96 offset:2048
	ds_read_b128 v[110:113], v96 offset:3072
	s_add_u32 s30, s46, 0x30000
	s_addc_u32 s31, s47, 0
	s_mov_b32 m0, s74
	v_lshl_add_u64 v[146:147], s[30:31], 0, v[140:141]
	ds_read_b128 v[114:117], v228 offset:32768
	ds_read_b128 v[118:121], v228 offset:33792
	ds_read_b128 v[122:125], v228 offset:34816
	ds_read_b128 v[126:129], v228 offset:35840
	ds_read_b128 v[130:133], v228 offset:36864
	ds_read_b128 v[134:137], v228 offset:37888
	global_load_lds_dwordx4 v[146:147], off
	v_lshl_add_u64 v[146:147], s[30:31], 0, v[138:139]
	s_mov_b32 m0, s75
	s_nop 0
	global_load_lds_dwordx4 v[146:147], off
	s_waitcnt lgkmcnt(6)
	s_barrier
	s_waitcnt lgkmcnt(0)
	s_setprio 1
	s_waitcnt lgkmcnt(0)
	v_mfma_f32_16x16x32_bf16 v[92:95], v[98:101], v[114:117], v[92:95]
	v_mfma_f32_16x16x32_bf16 v[68:71], v[106:109], v[114:117], v[68:71]
	v_mfma_f32_16x16x32_bf16 v[88:91], v[98:101], v[122:125], v[88:91]
	v_mfma_f32_16x16x32_bf16 v[64:67], v[106:109], v[122:125], v[64:67]
	v_mfma_f32_16x16x32_bf16 v[84:87], v[98:101], v[130:133], v[84:87]
	v_mfma_f32_16x16x32_bf16 v[60:63], v[106:109], v[130:133], v[60:63]
	v_mfma_f32_16x16x32_bf16 v[92:95], v[102:105], v[118:121], v[92:95]
	v_mfma_f32_16x16x32_bf16 v[68:71], v[110:113], v[118:121], v[68:71]
	v_mfma_f32_16x16x32_bf16 v[88:91], v[102:105], v[126:129], v[88:91]
	v_mfma_f32_16x16x32_bf16 v[64:67], v[110:113], v[126:129], v[64:67]
	v_mfma_f32_16x16x32_bf16 v[84:87], v[102:105], v[134:137], v[84:87]
	v_mfma_f32_16x16x32_bf16 v[60:63], v[110:113], v[134:137], v[60:63]
	s_setprio 0
	s_barrier
	s_add_i32 s43, 0, 0x1c000
	s_add_i32 s30, s42, s37
	v_add_u32_e32 v96, s43, v203
	v_lshl_add_u64 v[162:163], v[162:163], 0, s[56:57]
	s_mov_b32 m0, s30
	ds_read_b128 v[146:149], v96
	ds_read_b128 v[150:153], v96 offset:1024
	ds_read_b128 v[154:157], v96 offset:2048
	ds_read_b128 v[158:161], v96 offset:3072
	global_load_lds_dwordx4 v[162:163], off
	v_lshl_add_u64 v[162:163], v[164:165], 0, s[56:57]
	s_add_i32 m0, s30, 0x2000
	s_nop 0
	global_load_lds_dwordx4 v[162:163], off
	s_barrier
	s_waitcnt lgkmcnt(0)
	s_setprio 1
	s_waitcnt lgkmcnt(0)
	v_mfma_f32_16x16x32_bf16 v[44:47], v[146:149], v[114:117], v[44:47]
	v_mfma_f32_16x16x32_bf16 v[20:23], v[154:157], v[114:117], v[20:23]
	v_mfma_f32_16x16x32_bf16 v[40:43], v[146:149], v[122:125], v[40:43]
	v_mfma_f32_16x16x32_bf16 v[16:19], v[154:157], v[122:125], v[16:19]
	v_mfma_f32_16x16x32_bf16 v[36:39], v[146:149], v[130:133], v[36:39]
	v_mfma_f32_16x16x32_bf16 v[12:15], v[154:157], v[130:133], v[12:15]
	v_mfma_f32_16x16x32_bf16 v[44:47], v[150:153], v[118:121], v[44:47]
	v_mfma_f32_16x16x32_bf16 v[20:23], v[158:161], v[118:121], v[20:23]
	v_mfma_f32_16x16x32_bf16 v[40:43], v[150:153], v[126:129], v[40:43]
	v_mfma_f32_16x16x32_bf16 v[16:19], v[158:161], v[126:129], v[16:19]
	v_mfma_f32_16x16x32_bf16 v[36:39], v[150:153], v[134:137], v[36:39]
	v_mfma_f32_16x16x32_bf16 v[12:15], v[158:161], v[134:137], v[12:15]
	s_setprio 0
	s_mov_b32 m0, s77
	v_lshl_add_u64 v[162:163], v[166:167], 0, s[56:57]
	s_barrier
	ds_read_b128 v[114:117], v228 offset:49152
	ds_read_b128 v[118:121], v228 offset:50176
	ds_read_b128 v[122:125], v228 offset:51200
	ds_read_b128 v[126:129], v228 offset:52224
	ds_read_b128 v[130:133], v228 offset:53248
	ds_read_b128 v[134:137], v228 offset:54272
	global_load_lds_dwordx4 v[162:163], off
	v_lshl_add_u64 v[162:163], v[168:169], 0, s[56:57]
	s_mov_b32 m0, s78
	s_nop 0
	global_load_lds_dwordx4 v[162:163], off
	s_barrier
	s_waitcnt lgkmcnt(0)
	s_setprio 1
	s_waitcnt lgkmcnt(0)
	v_mfma_f32_16x16x32_bf16 v[80:83], v[98:101], v[114:117], v[80:83]
	v_mfma_f32_16x16x32_bf16 v[56:59], v[106:109], v[114:117], v[56:59]
	v_mfma_f32_16x16x32_bf16 v[76:79], v[98:101], v[122:125], v[76:79]
	v_mfma_f32_16x16x32_bf16 v[52:55], v[106:109], v[122:125], v[52:55]
	v_mfma_f32_16x16x32_bf16 v[72:75], v[98:101], v[130:133], v[72:75]
	v_mfma_f32_16x16x32_bf16 v[48:51], v[106:109], v[130:133], v[48:51]
	v_mfma_f32_16x16x32_bf16 v[80:83], v[102:105], v[118:121], v[80:83]
	v_mfma_f32_16x16x32_bf16 v[56:59], v[110:113], v[118:121], v[56:59]
	v_mfma_f32_16x16x32_bf16 v[76:79], v[102:105], v[126:129], v[76:79]
	v_mfma_f32_16x16x32_bf16 v[52:55], v[110:113], v[126:129], v[52:55]
	v_mfma_f32_16x16x32_bf16 v[72:75], v[102:105], v[134:137], v[72:75]
	v_mfma_f32_16x16x32_bf16 v[48:51], v[110:113], v[134:137], v[48:51]
	s_setprio 0
	s_barrier
	s_add_u32 s30, s44, 0x40080
	s_addc_u32 s31, s45, 0
	s_add_i32 s42, s43, s37
	v_lshl_add_u64 v[98:99], s[30:31], 0, v[140:141]
	s_mov_b32 m0, s42
	s_nop 0
	global_load_lds_dwordx4 v[98:99], off
	v_lshl_add_u64 v[98:99], s[30:31], 0, v[138:139]
	s_add_i32 m0, s42, 0x2000
	s_nop 0
	global_load_lds_dwordx4 v[98:99], off
	s_waitcnt vmcnt(6)
	s_barrier
	s_setprio 1
	v_mfma_f32_16x16x32_bf16 v[32:35], v[146:149], v[114:117], v[32:35]
	v_mfma_f32_16x16x32_bf16 v[8:11], v[154:157], v[114:117], v[8:11]
	v_mfma_f32_16x16x32_bf16 v[28:31], v[146:149], v[122:125], v[28:31]
	v_mfma_f32_16x16x32_bf16 v[4:7], v[154:157], v[122:125], v[4:7]
	v_mfma_f32_16x16x32_bf16 v[24:27], v[146:149], v[130:133], v[24:27]
	v_mfma_f32_16x16x32_bf16 v[0:3], v[154:157], v[130:133], v[0:3]
	v_mfma_f32_16x16x32_bf16 v[32:35], v[150:153], v[118:121], v[32:35]
	v_mfma_f32_16x16x32_bf16 v[8:11], v[158:161], v[118:121], v[8:11]
	v_mfma_f32_16x16x32_bf16 v[28:31], v[150:153], v[126:129], v[28:31]
	v_mfma_f32_16x16x32_bf16 v[4:7], v[158:161], v[126:129], v[4:7]
	v_mfma_f32_16x16x32_bf16 v[24:27], v[150:153], v[134:137], v[24:27]
	v_mfma_f32_16x16x32_bf16 v[0:3], v[158:161], v[134:137], v[0:3]
	s_setprio 0
	s_add_i32 s61, s61, 2
	s_add_u32 s52, s52, 0x100
	s_addc_u32 s53, s53, 0
	s_cmp_gt_u32 s61, 13
	s_mov_b64 s[30:31], s[0:1]
	s_barrier
	s_cbranch_scc0 .LBB0_107
	s_mul_i32 s43, s48, 0xc0
	s_add_i32 s44, s43, s80
	v_add_u32_e32 v231, s44, v202
	s_lshl_b32 s44, s49, 8
	s_or_b32 s44, s44, s76
	v_lshl_add_u32 v233, v171, 2, s44
	s_add_i32 s44, s43, 0xffffe000
	s_ashr_i32 s45, s44, 11
	s_add_i32 s45, s45, 1
	s_max_i32 s45, s45, 0
	s_addk_i32 s44, 0xbf
	s_ashr_i32 s44, s44, 11
	s_add_i32 s44, s44, 1
	s_max_i32 s44, s44, 0
	s_lshl_b32 s46, s45, 11
	s_addk_i32 s46, 0x2000
	s_lshl_b32 s46, s46, 12
	s_cmp_lg_u32 s44, s45
	s_cselect_b32 s42, s46, -1
	s_cselect_b32 s47, 0x9000, 0
	s_mul_i32 s45, s45, 0x9000
	s_add_u32 s0, s58, s45
	s_addc_u32 s1, s59, 0
	s_add_u32 s30, s0, s47
	s_addc_u32 s31, s1, 0
	v_lshlrev_b32_e32 v96, 2, v233
	v_lshl_add_u32 v206, v231, 12, v96
	v_add_u32_e32 v207, 0x10000, v206
	v_add_u32_e32 v208, 0x20000, v206
	v_add_u32_e32 v209, 0x60000, v206
	v_add_u32_e32 v216, 0x70000, v206
	v_add_u32_e32 v217, 0x80000, v206
	global_load_dwordx4 v[184:187], v96, s[0:1] offset:0
	global_load_dwordx4 v[188:191], v96, s[30:31] offset:0
	global_load_dwordx4 v[98:101], v206, s[90:91] offset:0
	global_load_dwordx4 v[102:105], v207, s[90:91] offset:0
	global_load_dwordx4 v[106:109], v208, s[90:91] offset:0
	global_load_dwordx4 v[110:113], v209, s[90:91] offset:0
	global_load_dwordx4 v[114:117], v216, s[90:91] offset:0
	global_load_dwordx4 v[118:121], v217, s[90:91] offset:0
	global_load_dwordx4 v[192:195], v96, s[0:1] offset:64
	global_load_dwordx4 v[196:199], v96, s[30:31] offset:64
	global_load_dwordx4 v[122:125], v206, s[90:91] offset:64
	global_load_dwordx4 v[126:129], v207, s[90:91] offset:64
	global_load_dwordx4 v[130:133], v208, s[90:91] offset:64
	global_load_dwordx4 v[134:137], v209, s[90:91] offset:64
	global_load_dwordx4 v[150:153], v216, s[90:91] offset:64
	global_load_dwordx4 v[154:157], v217, s[90:91] offset:64
	global_load_dwordx4 v[158:161], v206, s[90:91] offset:512
	global_load_dwordx4 v[162:165], v207, s[90:91] offset:512
	global_load_dwordx4 v[166:169], v208, s[90:91] offset:512
	global_load_dwordx4 v[172:175], v209, s[90:91] offset:512
	global_load_dwordx4 v[176:179], v216, s[90:91] offset:512
	global_load_dwordx4 v[180:183], v217, s[90:91] offset:512
	v_cmp_le_u32_e64 s[44:45], s42, v206
	v_cmp_le_u32_e64 s[46:47], s42, v207
	v_cmp_le_u32_e64 s[48:49], s42, v208
	v_cmp_le_u32_e64 s[50:51], s42, v209
	v_cmp_le_u32_e64 s[52:53], s42, v216
	v_cmp_le_u32_e32 vcc, s42, v217
	s_waitcnt vmcnt(14)
	v_cndmask_b32_e64 v242, v184, v188, s[44:45]
	v_cndmask_b32_e64 v243, v185, v189, s[44:45]
	v_cndmask_b32_e64 v244, v186, v190, s[44:45]
	v_cndmask_b32_e64 v245, v187, v191, s[44:45]
	v_pk_fma_f32 v[92:93], v[92:93], v[242:243], v[98:99]
	v_pk_fma_f32 v[94:95], v[94:95], v[244:245], v[100:101]
	v_cndmask_b32_e64 v242, v184, v188, s[46:47]
	v_cndmask_b32_e64 v243, v185, v189, s[46:47]
	v_cndmask_b32_e64 v244, v186, v190, s[46:47]
	v_cndmask_b32_e64 v245, v187, v191, s[46:47]
	v_pk_fma_f32 v[88:89], v[88:89], v[242:243], v[102:103]
	v_pk_fma_f32 v[90:91], v[90:91], v[244:245], v[104:105]
	v_cndmask_b32_e64 v242, v184, v188, s[48:49]
	v_cndmask_b32_e64 v243, v185, v189, s[48:49]
	v_cndmask_b32_e64 v244, v186, v190, s[48:49]
	v_cndmask_b32_e64 v245, v187, v191, s[48:49]
	v_pk_fma_f32 v[84:85], v[84:85], v[242:243], v[106:107]
	v_pk_fma_f32 v[86:87], v[86:87], v[244:245], v[108:109]
	v_cndmask_b32_e64 v242, v184, v188, s[50:51]
	v_cndmask_b32_e64 v243, v185, v189, s[50:51]
	v_cndmask_b32_e64 v244, v186, v190, s[50:51]
	v_cndmask_b32_e64 v245, v187, v191, s[50:51]
	v_pk_fma_f32 v[80:81], v[80:81], v[242:243], v[110:111]
	v_pk_fma_f32 v[82:83], v[82:83], v[244:245], v[112:113]
	v_cndmask_b32_e64 v242, v184, v188, s[52:53]
	v_cndmask_b32_e64 v243, v185, v189, s[52:53]
	v_cndmask_b32_e64 v244, v186, v190, s[52:53]
	v_cndmask_b32_e64 v245, v187, v191, s[52:53]
	v_pk_fma_f32 v[76:77], v[76:77], v[242:243], v[114:115]
	v_pk_fma_f32 v[78:79], v[78:79], v[244:245], v[116:117]
	v_cndmask_b32_e32 v242, v184, v188, vcc
	v_cndmask_b32_e32 v243, v185, v189, vcc
	v_cndmask_b32_e32 v244, v186, v190, vcc
	v_cndmask_b32_e32 v245, v187, v191, vcc
	v_pk_fma_f32 v[72:73], v[72:73], v[242:243], v[118:119]
	v_pk_fma_f32 v[74:75], v[74:75], v[244:245], v[120:121]
	global_load_dwordx4 v[98:101], v206, s[90:91] offset:576
	global_load_dwordx4 v[102:105], v207, s[90:91] offset:576
	global_load_dwordx4 v[106:109], v208, s[90:91] offset:576
	global_load_dwordx4 v[110:113], v209, s[90:91] offset:576
	global_load_dwordx4 v[114:117], v216, s[90:91] offset:576
	global_load_dwordx4 v[118:121], v217, s[90:91] offset:576
	global_load_dwordx4 v[184:187], v96, s[0:1] offset:512
	global_load_dwordx4 v[188:191], v96, s[30:31] offset:512
	global_load_dwordx4 v[234:237], v96, s[0:1] offset:576
	global_load_dwordx4 v[238:241], v96, s[30:31] offset:576
	s_waitcnt vmcnt(16)
	v_cndmask_b32_e64 v242, v192, v196, s[44:45]
	v_cndmask_b32_e64 v243, v193, v197, s[44:45]
	v_cndmask_b32_e64 v244, v194, v198, s[44:45]
	v_cndmask_b32_e64 v245, v195, v199, s[44:45]
	v_pk_fma_f32 v[68:69], v[68:69], v[242:243], v[122:123]
	v_pk_fma_f32 v[70:71], v[70:71], v[244:245], v[124:125]
	v_cndmask_b32_e64 v242, v192, v196, s[46:47]
	v_cndmask_b32_e64 v243, v193, v197, s[46:47]
	v_cndmask_b32_e64 v244, v194, v198, s[46:47]
	v_cndmask_b32_e64 v245, v195, v199, s[46:47]
	v_pk_fma_f32 v[64:65], v[64:65], v[242:243], v[126:127]
	v_pk_fma_f32 v[66:67], v[66:67], v[244:245], v[128:129]
	v_cndmask_b32_e64 v242, v192, v196, s[48:49]
	v_cndmask_b32_e64 v243, v193, v197, s[48:49]
	v_cndmask_b32_e64 v244, v194, v198, s[48:49]
	v_cndmask_b32_e64 v245, v195, v199, s[48:49]
	v_pk_fma_f32 v[60:61], v[60:61], v[242:243], v[130:131]
	v_pk_fma_f32 v[62:63], v[62:63], v[244:245], v[132:133]
	v_cndmask_b32_e64 v242, v192, v196, s[50:51]
	v_cndmask_b32_e64 v243, v193, v197, s[50:51]
	v_cndmask_b32_e64 v244, v194, v198, s[50:51]
	v_cndmask_b32_e64 v245, v195, v199, s[50:51]
	v_pk_fma_f32 v[56:57], v[56:57], v[242:243], v[134:135]
	v_pk_fma_f32 v[58:59], v[58:59], v[244:245], v[136:137]
	v_cndmask_b32_e64 v242, v192, v196, s[52:53]
	v_cndmask_b32_e64 v243, v193, v197, s[52:53]
	v_cndmask_b32_e64 v244, v194, v198, s[52:53]
	v_cndmask_b32_e64 v245, v195, v199, s[52:53]
	v_pk_fma_f32 v[52:53], v[52:53], v[242:243], v[150:151]
	v_pk_fma_f32 v[54:55], v[54:55], v[244:245], v[152:153]
	v_cndmask_b32_e32 v242, v192, v196, vcc
	v_cndmask_b32_e32 v243, v193, v197, vcc
	v_cndmask_b32_e32 v244, v194, v198, vcc
	v_cndmask_b32_e32 v245, v195, v199, vcc
	v_pk_fma_f32 v[48:49], v[48:49], v[242:243], v[154:155]
	v_pk_fma_f32 v[50:51], v[50:51], v[244:245], v[156:157]
	s_waitcnt vmcnt(0)
	v_cndmask_b32_e64 v242, v184, v188, s[44:45]
	v_cndmask_b32_e64 v243, v185, v189, s[44:45]
	v_cndmask_b32_e64 v244, v186, v190, s[44:45]
	v_cndmask_b32_e64 v245, v187, v191, s[44:45]
	v_pk_fma_f32 v[44:45], v[44:45], v[242:243], v[158:159]
	v_pk_fma_f32 v[46:47], v[46:47], v[244:245], v[160:161]
	v_cndmask_b32_e64 v242, v184, v188, s[46:47]
	v_cndmask_b32_e64 v243, v185, v189, s[46:47]
	v_cndmask_b32_e64 v244, v186, v190, s[46:47]
	v_cndmask_b32_e64 v245, v187, v191, s[46:47]
	v_pk_fma_f32 v[40:41], v[40:41], v[242:243], v[162:163]
	v_pk_fma_f32 v[42:43], v[42:43], v[244:245], v[164:165]
	v_cndmask_b32_e64 v242, v184, v188, s[48:49]
	v_cndmask_b32_e64 v243, v185, v189, s[48:49]
	v_cndmask_b32_e64 v244, v186, v190, s[48:49]
	v_cndmask_b32_e64 v245, v187, v191, s[48:49]
	v_pk_fma_f32 v[36:37], v[36:37], v[242:243], v[166:167]
	v_pk_fma_f32 v[38:39], v[38:39], v[244:245], v[168:169]
	v_cndmask_b32_e64 v242, v184, v188, s[50:51]
	v_cndmask_b32_e64 v243, v185, v189, s[50:51]
	v_cndmask_b32_e64 v244, v186, v190, s[50:51]
	v_cndmask_b32_e64 v245, v187, v191, s[50:51]
	v_pk_fma_f32 v[32:33], v[32:33], v[242:243], v[172:173]
	v_pk_fma_f32 v[34:35], v[34:35], v[244:245], v[174:175]
	v_cndmask_b32_e64 v242, v184, v188, s[52:53]
	v_cndmask_b32_e64 v243, v185, v189, s[52:53]
	v_cndmask_b32_e64 v244, v186, v190, s[52:53]
	v_cndmask_b32_e64 v245, v187, v191, s[52:53]
	v_pk_fma_f32 v[28:29], v[28:29], v[242:243], v[176:177]
	v_pk_fma_f32 v[30:31], v[30:31], v[244:245], v[178:179]
	v_cndmask_b32_e32 v242, v184, v188, vcc
	v_cndmask_b32_e32 v243, v185, v189, vcc
	v_cndmask_b32_e32 v244, v186, v190, vcc
	v_cndmask_b32_e32 v245, v187, v191, vcc
	v_pk_fma_f32 v[24:25], v[24:25], v[242:243], v[180:181]
	v_pk_fma_f32 v[26:27], v[26:27], v[244:245], v[182:183]
	v_cndmask_b32_e64 v242, v234, v238, s[44:45]
	v_cndmask_b32_e64 v243, v235, v239, s[44:45]
	v_cndmask_b32_e64 v244, v236, v240, s[44:45]
	v_cndmask_b32_e64 v245, v237, v241, s[44:45]
	v_pk_fma_f32 v[20:21], v[20:21], v[242:243], v[98:99]
	v_pk_fma_f32 v[22:23], v[22:23], v[244:245], v[100:101]
	v_cndmask_b32_e64 v242, v234, v238, s[46:47]
	v_cndmask_b32_e64 v243, v235, v239, s[46:47]
	v_cndmask_b32_e64 v244, v236, v240, s[46:47]
	v_cndmask_b32_e64 v245, v237, v241, s[46:47]
	v_pk_fma_f32 v[16:17], v[16:17], v[242:243], v[102:103]
	v_pk_fma_f32 v[18:19], v[18:19], v[244:245], v[104:105]
	v_cndmask_b32_e64 v242, v234, v238, s[48:49]
	v_cndmask_b32_e64 v243, v235, v239, s[48:49]
	v_cndmask_b32_e64 v244, v236, v240, s[48:49]
	v_cndmask_b32_e64 v245, v237, v241, s[48:49]
	v_pk_fma_f32 v[12:13], v[12:13], v[242:243], v[106:107]
	v_pk_fma_f32 v[14:15], v[14:15], v[244:245], v[108:109]
	v_cndmask_b32_e64 v242, v234, v238, s[50:51]
	v_cndmask_b32_e64 v243, v235, v239, s[50:51]
	v_cndmask_b32_e64 v244, v236, v240, s[50:51]
	v_cndmask_b32_e64 v245, v237, v241, s[50:51]
	v_pk_fma_f32 v[8:9], v[8:9], v[242:243], v[110:111]
	v_pk_fma_f32 v[10:11], v[10:11], v[244:245], v[112:113]
	v_cndmask_b32_e64 v242, v234, v238, s[52:53]
	v_cndmask_b32_e64 v243, v235, v239, s[52:53]
	v_cndmask_b32_e64 v244, v236, v240, s[52:53]
	v_cndmask_b32_e64 v245, v237, v241, s[52:53]
	v_pk_fma_f32 v[4:5], v[4:5], v[242:243], v[114:115]
	v_pk_fma_f32 v[6:7], v[6:7], v[244:245], v[116:117]
	v_cndmask_b32_e32 v242, v234, v238, vcc
	v_cndmask_b32_e32 v243, v235, v239, vcc
	v_cndmask_b32_e32 v244, v236, v240, vcc
	v_cndmask_b32_e32 v245, v237, v241, vcc
	v_pk_fma_f32 v[0:1], v[0:1], v[242:243], v[118:119]
	v_pk_fma_f32 v[2:3], v[2:3], v[244:245], v[120:121]
	global_store_dwordx4 v206, v[92:95], s[90:91] offset:0
	global_store_dwordx4 v207, v[88:91], s[90:91] offset:0
	global_store_dwordx4 v208, v[84:87], s[90:91] offset:0
	global_store_dwordx4 v209, v[80:83], s[90:91] offset:0
	global_store_dwordx4 v216, v[76:79], s[90:91] offset:0
	global_store_dwordx4 v217, v[72:75], s[90:91] offset:0
	global_store_dwordx4 v206, v[68:71], s[90:91] offset:64
	global_store_dwordx4 v207, v[64:67], s[90:91] offset:64
	global_store_dwordx4 v208, v[60:63], s[90:91] offset:64
	global_store_dwordx4 v209, v[56:59], s[90:91] offset:64
	global_store_dwordx4 v216, v[52:55], s[90:91] offset:64
	global_store_dwordx4 v217, v[48:51], s[90:91] offset:64
	global_store_dwordx4 v206, v[44:47], s[90:91] offset:512
	global_store_dwordx4 v207, v[40:43], s[90:91] offset:512
	global_store_dwordx4 v208, v[36:39], s[90:91] offset:512
	global_store_dwordx4 v209, v[32:35], s[90:91] offset:512
	global_store_dwordx4 v216, v[28:31], s[90:91] offset:512
	global_store_dwordx4 v217, v[24:27], s[90:91] offset:512
	global_store_dwordx4 v206, v[20:23], s[90:91] offset:576
	global_store_dwordx4 v207, v[16:19], s[90:91] offset:576
	global_store_dwordx4 v208, v[12:15], s[90:91] offset:576
	global_store_dwordx4 v209, v[8:11], s[90:91] offset:576
	global_store_dwordx4 v216, v[4:7], s[90:91] offset:576
	global_store_dwordx4 v217, v[0:3], s[90:91] offset:576
	s_branch .LBB0_97

.Lp0_tramp:
	s_branch .Lp0_reenter

.LBB0_482:
	s_add_u32 s0, s30, 0x100
	s_addc_u32 s1, s31, 0
	s_add_i32 s42, 0, 0x10000
	v_add_u32_e32 v96, s42, v229
	ds_read_b128 v[98:101], v96
	ds_read_b128 v[102:105], v96 offset:1024
	ds_read_b128 v[106:109], v96 offset:2048
	ds_read_b128 v[110:113], v96 offset:3072
	s_cmp_eq_u32 s52, 40
	s_cselect_b32 s47, s71, s1
	s_cselect_b32 s46, s70, s0
	s_cselect_b32 s45, s97, s51
	s_cselect_b32 s44, s96, s50
	v_lshl_add_u64 v[138:139], s[30:31], 0, v[146:147]
	s_add_i32 m0, s72, 0xc000
	ds_read_b128 v[114:117], v230
	ds_read_b128 v[118:121], v230 offset:1024
	ds_read_b128 v[122:125], v230 offset:2048
	ds_read_b128 v[126:129], v230 offset:3072
	ds_read_b128 v[130:133], v230 offset:4096
	ds_read_b128 v[134:137], v230 offset:5120
	global_load_lds_dwordx4 v[138:139], off
	v_lshl_add_u64 v[138:139], s[30:31], 0, v[148:149]
	s_add_i32 m0, s72, 0xe000
	s_nop 0
	global_load_lds_dwordx4 v[138:139], off
	s_waitcnt lgkmcnt(6)
	s_barrier
	s_waitcnt lgkmcnt(0)
	s_setprio 1
	s_waitcnt lgkmcnt(0)
	v_mfma_f32_16x16x32_bf16 v[92:95], v[98:101], v[114:117], v[92:95]
	v_mfma_f32_16x16x32_bf16 v[80:83], v[106:109], v[114:117], v[80:83]
	v_mfma_f32_16x16x32_bf16 v[88:91], v[98:101], v[122:125], v[88:91]
	v_mfma_f32_16x16x32_bf16 v[68:71], v[106:109], v[122:125], v[68:71]
	v_mfma_f32_16x16x32_bf16 v[84:87], v[98:101], v[130:133], v[84:87]
	v_mfma_f32_16x16x32_bf16 v[60:63], v[106:109], v[130:133], v[60:63]
	v_mfma_f32_16x16x32_bf16 v[92:95], v[102:105], v[118:121], v[92:95]
	v_mfma_f32_16x16x32_bf16 v[80:83], v[110:113], v[118:121], v[80:83]
	v_mfma_f32_16x16x32_bf16 v[88:91], v[102:105], v[126:129], v[88:91]
	v_mfma_f32_16x16x32_bf16 v[68:71], v[110:113], v[126:129], v[68:71]
	v_mfma_f32_16x16x32_bf16 v[84:87], v[102:105], v[134:137], v[84:87]
	v_mfma_f32_16x16x32_bf16 v[60:63], v[110:113], v[134:137], v[60:63]
	s_setprio 0
	s_barrier
	s_add_i32 s43, 0, 0x14000
	s_add_i32 s30, s42, s37
	v_add_u32_e32 v96, s43, v229
	v_lshl_add_u64 v[162:163], s[44:45], 0, v[144:145]
	s_mov_b32 m0, s30
	ds_read_b128 v[138:141], v96
	ds_read_b128 v[150:153], v96 offset:1024
	ds_read_b128 v[154:157], v96 offset:2048
	ds_read_b128 v[158:161], v96 offset:3072
	global_load_lds_dwordx4 v[162:163], off
	v_lshl_add_u64 v[166:167], s[44:45], 0, v[142:143]
	s_add_i32 m0, s30, 0x2000
	s_nop 0
	global_load_lds_dwordx4 v[166:167], off
	s_barrier
	s_waitcnt lgkmcnt(0)
	s_setprio 1
	s_waitcnt lgkmcnt(0)
	v_mfma_f32_16x16x32_bf16 v[48:51], v[138:141], v[114:117], v[48:51]
	v_mfma_f32_16x16x32_bf16 v[28:31], v[154:157], v[114:117], v[28:31]
	v_mfma_f32_16x16x32_bf16 v[40:43], v[138:141], v[122:125], v[40:43]
	v_mfma_f32_16x16x32_bf16 v[20:23], v[154:157], v[122:125], v[20:23]
	v_mfma_f32_16x16x32_bf16 v[36:39], v[138:141], v[130:133], v[36:39]
	v_mfma_f32_16x16x32_bf16 v[12:15], v[154:157], v[130:133], v[12:15]
	v_mfma_f32_16x16x32_bf16 v[48:51], v[150:153], v[118:121], v[48:51]
	v_mfma_f32_16x16x32_bf16 v[28:31], v[158:161], v[118:121], v[28:31]
	v_mfma_f32_16x16x32_bf16 v[40:43], v[150:153], v[126:129], v[40:43]
	v_mfma_f32_16x16x32_bf16 v[20:23], v[158:161], v[126:129], v[20:23]
	v_mfma_f32_16x16x32_bf16 v[36:39], v[150:153], v[134:137], v[36:39]
	v_mfma_f32_16x16x32_bf16 v[12:15], v[158:161], v[134:137], v[12:15]
	s_setprio 0
	s_mov_b32 m0, s72
	v_lshl_add_u64 v[168:169], s[46:47], 0, v[144:145]
	s_barrier
	ds_read_b128 v[114:117], v230 offset:16384
	ds_read_b128 v[118:121], v230 offset:17408
	ds_read_b128 v[122:125], v230 offset:18432
	ds_read_b128 v[126:129], v230 offset:19456
	ds_read_b128 v[130:133], v230 offset:20480
	ds_read_b128 v[134:137], v230 offset:21504
	global_load_lds_dwordx4 v[168:169], off
	v_lshl_add_u64 v[174:175], s[46:47], 0, v[142:143]
	s_mov_b32 m0, s73
	s_nop 0
	global_load_lds_dwordx4 v[174:175], off
	s_barrier
	s_waitcnt lgkmcnt(0)
	s_setprio 1
	s_waitcnt lgkmcnt(0)
	v_mfma_f32_16x16x32_bf16 v[76:79], v[98:101], v[114:117], v[76:79]
	v_mfma_f32_16x16x32_bf16 v[56:59], v[106:109], v[114:117], v[56:59]
	v_mfma_f32_16x16x32_bf16 v[72:75], v[98:101], v[122:125], v[72:75]
	v_mfma_f32_16x16x32_bf16 v[52:55], v[106:109], v[122:125], v[52:55]
	v_mfma_f32_16x16x32_bf16 v[64:67], v[98:101], v[130:133], v[64:67]
	v_mfma_f32_16x16x32_bf16 v[44:47], v[106:109], v[130:133], v[44:47]
	v_mfma_f32_16x16x32_bf16 v[76:79], v[102:105], v[118:121], v[76:79]
	v_mfma_f32_16x16x32_bf16 v[56:59], v[110:113], v[118:121], v[56:59]
	v_mfma_f32_16x16x32_bf16 v[72:75], v[102:105], v[126:129], v[72:75]
	v_mfma_f32_16x16x32_bf16 v[52:55], v[110:113], v[126:129], v[52:55]
	v_mfma_f32_16x16x32_bf16 v[64:67], v[102:105], v[134:137], v[64:67]
	v_mfma_f32_16x16x32_bf16 v[44:47], v[110:113], v[134:137], v[44:47]
	s_setprio 0
	s_barrier
	s_add_u32 s30, s44, 0xb0000
	s_addc_u32 s31, s45, 0
	s_add_i32 s42, s43, s37
	v_lshl_add_u64 v[98:99], s[30:31], 0, v[144:145]
	s_mov_b32 m0, s42
	s_nop 0
	global_load_lds_dwordx4 v[98:99], off
	v_lshl_add_u64 v[98:99], s[30:31], 0, v[142:143]
	s_add_i32 m0, s42, 0x2000
	s_nop 0
	global_load_lds_dwordx4 v[98:99], off
	s_waitcnt vmcnt(6)
	s_barrier
	s_setprio 1
	v_mfma_f32_16x16x32_bf16 v[32:35], v[138:141], v[114:117], v[32:35]
	v_mfma_f32_16x16x32_bf16 v[8:11], v[154:157], v[114:117], v[8:11]
	v_mfma_f32_16x16x32_bf16 v[24:27], v[138:141], v[122:125], v[24:27]
	v_mfma_f32_16x16x32_bf16 v[4:7], v[154:157], v[122:125], v[4:7]
	v_mfma_f32_16x16x32_bf16 v[16:19], v[138:141], v[130:133], v[16:19]
	v_mfma_f32_16x16x32_bf16 v[0:3], v[154:157], v[130:133], v[0:3]
	v_mfma_f32_16x16x32_bf16 v[32:35], v[150:153], v[118:121], v[32:35]
	v_mfma_f32_16x16x32_bf16 v[8:11], v[158:161], v[118:121], v[8:11]
	v_mfma_f32_16x16x32_bf16 v[24:27], v[150:153], v[126:129], v[24:27]
	v_mfma_f32_16x16x32_bf16 v[4:7], v[158:161], v[126:129], v[4:7]
	v_mfma_f32_16x16x32_bf16 v[16:19], v[150:153], v[134:137], v[16:19]
	v_mfma_f32_16x16x32_bf16 v[0:3], v[158:161], v[134:137], v[0:3]
	s_setprio 0
	s_add_i32 s42, 0, 0x18000
	v_add_u32_e32 v96, s42, v229
	s_barrier
	ds_read_b128 v[98:101], v96
	ds_read_b128 v[102:105], v96 offset:1024
	ds_read_b128 v[106:109], v96 offset:2048
	ds_read_b128 v[110:113], v96 offset:3072
	s_add_u32 s30, s46, 0x84000
	s_addc_u32 s31, s47, 0
	s_mov_b32 m0, s74
	v_lshl_add_u64 v[138:139], s[30:31], 0, v[144:145]
	ds_read_b128 v[114:117], v230 offset:32768
	ds_read_b128 v[118:121], v230 offset:33792
	ds_read_b128 v[122:125], v230 offset:34816
	ds_read_b128 v[126:129], v230 offset:35840
	ds_read_b128 v[130:133], v230 offset:36864
	ds_read_b128 v[134:137], v230 offset:37888
	global_load_lds_dwordx4 v[138:139], off
	v_lshl_add_u64 v[138:139], s[30:31], 0, v[142:143]
	s_mov_b32 m0, s75
	s_nop 0
	global_load_lds_dwordx4 v[138:139], off
	s_waitcnt lgkmcnt(6)
	s_barrier
	s_waitcnt lgkmcnt(0)
	s_setprio 1
	s_waitcnt lgkmcnt(0)
	v_mfma_f32_16x16x32_bf16 v[92:95], v[98:101], v[114:117], v[92:95]
	v_mfma_f32_16x16x32_bf16 v[80:83], v[106:109], v[114:117], v[80:83]
	v_mfma_f32_16x16x32_bf16 v[88:91], v[98:101], v[122:125], v[88:91]
	v_mfma_f32_16x16x32_bf16 v[68:71], v[106:109], v[122:125], v[68:71]
	v_mfma_f32_16x16x32_bf16 v[84:87], v[98:101], v[130:133], v[84:87]
	v_mfma_f32_16x16x32_bf16 v[60:63], v[106:109], v[130:133], v[60:63]
	v_mfma_f32_16x16x32_bf16 v[92:95], v[102:105], v[118:121], v[92:95]
	v_mfma_f32_16x16x32_bf16 v[80:83], v[110:113], v[118:121], v[80:83]
	v_mfma_f32_16x16x32_bf16 v[88:91], v[102:105], v[126:129], v[88:91]
	v_mfma_f32_16x16x32_bf16 v[68:71], v[110:113], v[126:129], v[68:71]
	v_mfma_f32_16x16x32_bf16 v[84:87], v[102:105], v[134:137], v[84:87]
	v_mfma_f32_16x16x32_bf16 v[60:63], v[110:113], v[134:137], v[60:63]
	s_setprio 0
	s_barrier
	s_add_i32 s43, 0, 0x1c000
	s_add_i32 s30, s42, s37
	v_add_u32_e32 v96, s43, v229
	v_lshl_add_u64 v[162:163], v[162:163], 0, s[56:57]
	s_mov_b32 m0, s30
	ds_read_b128 v[138:141], v96
	ds_read_b128 v[150:153], v96 offset:1024
	ds_read_b128 v[154:157], v96 offset:2048
	ds_read_b128 v[158:161], v96 offset:3072
	global_load_lds_dwordx4 v[162:163], off
	v_lshl_add_u64 v[162:163], v[166:167], 0, s[56:57]
	s_add_i32 m0, s30, 0x2000
	s_nop 0
	global_load_lds_dwordx4 v[162:163], off
	s_barrier
	s_waitcnt lgkmcnt(0)
	s_setprio 1
	s_waitcnt lgkmcnt(0)
	v_mfma_f32_16x16x32_bf16 v[48:51], v[138:141], v[114:117], v[48:51]
	v_mfma_f32_16x16x32_bf16 v[28:31], v[154:157], v[114:117], v[28:31]
	v_mfma_f32_16x16x32_bf16 v[40:43], v[138:141], v[122:125], v[40:43]
	v_mfma_f32_16x16x32_bf16 v[20:23], v[154:157], v[122:125], v[20:23]
	v_mfma_f32_16x16x32_bf16 v[36:39], v[138:141], v[130:133], v[36:39]
	v_mfma_f32_16x16x32_bf16 v[12:15], v[154:157], v[130:133], v[12:15]
	v_mfma_f32_16x16x32_bf16 v[48:51], v[150:153], v[118:121], v[48:51]
	v_mfma_f32_16x16x32_bf16 v[28:31], v[158:161], v[118:121], v[28:31]
	v_mfma_f32_16x16x32_bf16 v[40:43], v[150:153], v[126:129], v[40:43]
	v_mfma_f32_16x16x32_bf16 v[20:23], v[158:161], v[126:129], v[20:23]
	v_mfma_f32_16x16x32_bf16 v[36:39], v[150:153], v[134:137], v[36:39]
	v_mfma_f32_16x16x32_bf16 v[12:15], v[158:161], v[134:137], v[12:15]
	s_setprio 0
	s_mov_b32 m0, s77
	v_lshl_add_u64 v[162:163], v[168:169], 0, s[56:57]
	s_barrier
	ds_read_b128 v[114:117], v230 offset:49152
	ds_read_b128 v[118:121], v230 offset:50176
	ds_read_b128 v[122:125], v230 offset:51200
	ds_read_b128 v[126:129], v230 offset:52224
	ds_read_b128 v[130:133], v230 offset:53248
	ds_read_b128 v[134:137], v230 offset:54272
	global_load_lds_dwordx4 v[162:163], off
	v_lshl_add_u64 v[162:163], v[174:175], 0, s[56:57]
	s_mov_b32 m0, s78
	s_nop 0
	global_load_lds_dwordx4 v[162:163], off
	s_barrier
	s_waitcnt lgkmcnt(0)
	s_setprio 1
	s_waitcnt lgkmcnt(0)
	v_mfma_f32_16x16x32_bf16 v[76:79], v[98:101], v[114:117], v[76:79]
	v_mfma_f32_16x16x32_bf16 v[56:59], v[106:109], v[114:117], v[56:59]
	v_mfma_f32_16x16x32_bf16 v[72:75], v[98:101], v[122:125], v[72:75]
	v_mfma_f32_16x16x32_bf16 v[52:55], v[106:109], v[122:125], v[52:55]
	v_mfma_f32_16x16x32_bf16 v[64:67], v[98:101], v[130:133], v[64:67]
	v_mfma_f32_16x16x32_bf16 v[44:47], v[106:109], v[130:133], v[44:47]
	v_mfma_f32_16x16x32_bf16 v[76:79], v[102:105], v[118:121], v[76:79]
	v_mfma_f32_16x16x32_bf16 v[56:59], v[110:113], v[118:121], v[56:59]
	v_mfma_f32_16x16x32_bf16 v[72:75], v[102:105], v[126:129], v[72:75]
	v_mfma_f32_16x16x32_bf16 v[52:55], v[110:113], v[126:129], v[52:55]
	v_mfma_f32_16x16x32_bf16 v[64:67], v[102:105], v[134:137], v[64:67]
	v_mfma_f32_16x16x32_bf16 v[44:47], v[110:113], v[134:137], v[44:47]
	s_setprio 0
	s_barrier
	s_add_u32 s30, s44, 0xb0080
	s_addc_u32 s31, s45, 0
	s_add_i32 s42, s43, s37
	v_lshl_add_u64 v[98:99], s[30:31], 0, v[144:145]
	s_mov_b32 m0, s42
	s_nop 0
	global_load_lds_dwordx4 v[98:99], off
	v_lshl_add_u64 v[98:99], s[30:31], 0, v[142:143]
	s_add_i32 m0, s42, 0x2000
	s_nop 0
	global_load_lds_dwordx4 v[98:99], off
	s_waitcnt vmcnt(6)
	s_barrier
	s_setprio 1
	v_mfma_f32_16x16x32_bf16 v[32:35], v[138:141], v[114:117], v[32:35]
	v_mfma_f32_16x16x32_bf16 v[8:11], v[154:157], v[114:117], v[8:11]
	v_mfma_f32_16x16x32_bf16 v[24:27], v[138:141], v[122:125], v[24:27]
	v_mfma_f32_16x16x32_bf16 v[4:7], v[154:157], v[122:125], v[4:7]
	v_mfma_f32_16x16x32_bf16 v[16:19], v[138:141], v[130:133], v[16:19]
	v_mfma_f32_16x16x32_bf16 v[0:3], v[154:157], v[130:133], v[0:3]
	v_mfma_f32_16x16x32_bf16 v[32:35], v[150:153], v[118:121], v[32:35]
	v_mfma_f32_16x16x32_bf16 v[8:11], v[158:161], v[118:121], v[8:11]
	v_mfma_f32_16x16x32_bf16 v[24:27], v[150:153], v[126:129], v[24:27]
	v_mfma_f32_16x16x32_bf16 v[4:7], v[158:161], v[126:129], v[4:7]
	v_mfma_f32_16x16x32_bf16 v[16:19], v[150:153], v[134:137], v[16:19]
	v_mfma_f32_16x16x32_bf16 v[0:3], v[158:161], v[134:137], v[0:3]
	s_setprio 0
	s_add_i32 s52, s52, 2
	s_add_u32 s50, s50, 0x100
	s_addc_u32 s51, s51, 0
	s_cmp_gt_u32 s52, 41
	s_mov_b64 s[30:31], s[0:1]
	s_barrier
	s_cbranch_scc0 .LBB0_482
	s_mul_i32 s43, s48, 0xc0
	s_add_i32 s44, s43, s80
	v_add_u32_e32 v231, s44, v228
	s_lshl_b32 s44, s49, 8
	s_or_b32 s44, s44, s76
	v_lshl_add_u32 v233, v171, 2, s44
	s_add_i32 s44, s43, 0xffffe000
	s_ashr_i32 s45, s44, 11
	s_add_i32 s45, s45, 1
	s_max_i32 s45, s45, 0
	s_addk_i32 s44, 0xbf
	s_ashr_i32 s44, s44, 11
	s_add_i32 s44, s44, 1
	s_max_i32 s44, s44, 0
	s_lshl_b32 s46, s45, 11
	s_addk_i32 s46, 0x2000
	s_lshl_b32 s46, s46, 12
	s_cmp_lg_u32 s44, s45
	s_cselect_b32 s42, s46, -1
	s_cselect_b32 s47, 0x9000, 0
	s_mul_i32 s45, s45, 0x9000
	s_add_u32 s0, s68, s45
	s_addc_u32 s1, s69, 0
	s_add_u32 s30, s0, s47
	s_addc_u32 s31, s1, 0
	v_lshlrev_b32_e32 v96, 2, v233
	v_lshl_add_u32 v206, v231, 12, v96
	v_add_u32_e32 v207, 0x10000, v206
	v_add_u32_e32 v208, 0x20000, v206
	v_add_u32_e32 v209, 0x60000, v206
	v_add_u32_e32 v216, 0x70000, v206
	v_add_u32_e32 v217, 0x80000, v206
	v_mov_b32_e32 v200, s58
	v_mov_b32_e32 v201, s59
	v_mov_b32_e32 v246, s81
	v_mov_b32_e32 v247, s3
	v_cmp_gt_u32_e32 vcc, 0x2000000, v206
	s_nop 1
	v_cndmask_b32_e32 v218, v246, v200, vcc
	v_cndmask_b32_e32 v219, v247, v201, vcc
	s_nop 0
	v_mad_u64_u32 v[218:219], s[52:53], v206, 1, v[218:219]
	v_cmp_gt_u32_e32 vcc, 0x2000000, v207
	s_nop 1
	v_cndmask_b32_e32 v220, v246, v200, vcc
	v_cndmask_b32_e32 v221, v247, v201, vcc
	s_nop 0
	v_mad_u64_u32 v[220:221], s[52:53], v207, 1, v[220:221]
	v_cmp_gt_u32_e32 vcc, 0x2000000, v208
	s_nop 1
	v_cndmask_b32_e32 v222, v246, v200, vcc
	v_cndmask_b32_e32 v223, v247, v201, vcc
	s_nop 0
	v_mad_u64_u32 v[222:223], s[52:53], v208, 1, v[222:223]
	v_cmp_gt_u32_e32 vcc, 0x2000000, v209
	s_nop 1
	v_cndmask_b32_e32 v224, v246, v200, vcc
	v_cndmask_b32_e32 v225, v247, v201, vcc
	s_nop 0
	v_mad_u64_u32 v[224:225], s[52:53], v209, 1, v[224:225]
	v_cmp_gt_u32_e32 vcc, 0x2000000, v216
	s_nop 1
	v_cndmask_b32_e32 v226, v246, v200, vcc
	v_cndmask_b32_e32 v227, v247, v201, vcc
	s_nop 0
	v_mad_u64_u32 v[226:227], s[52:53], v216, 1, v[226:227]
	v_cmp_gt_u32_e32 vcc, 0x2000000, v217
	s_nop 1
	v_cndmask_b32_e32 v232, v246, v200, vcc
	v_cndmask_b32_e32 v233, v247, v201, vcc
	s_nop 0
	v_mad_u64_u32 v[232:233], s[52:53], v217, 1, v[232:233]
	global_load_dwordx4 v[184:187], v96, s[0:1] offset:0
	global_load_dwordx4 v[188:191], v96, s[30:31] offset:0
	global_load_dwordx4 v[98:101], v[218:219], off offset:0
	global_load_dwordx4 v[102:105], v[220:221], off offset:0
	global_load_dwordx4 v[106:109], v[222:223], off offset:0
	global_load_dwordx4 v[110:113], v[224:225], off offset:0
	global_load_dwordx4 v[114:117], v[226:227], off offset:0
	global_load_dwordx4 v[118:121], v[232:233], off offset:0
	global_load_dwordx4 v[192:195], v96, s[0:1] offset:64
	global_load_dwordx4 v[196:199], v96, s[30:31] offset:64
	global_load_dwordx4 v[122:125], v[218:219], off offset:64
	global_load_dwordx4 v[126:129], v[220:221], off offset:64
	global_load_dwordx4 v[130:133], v[222:223], off offset:64
	global_load_dwordx4 v[134:137], v[224:225], off offset:64
	global_load_dwordx4 v[150:153], v[226:227], off offset:64
	global_load_dwordx4 v[154:157], v[232:233], off offset:64
	global_load_dwordx4 v[158:161], v[218:219], off offset:512
	global_load_dwordx4 v[162:165], v[220:221], off offset:512
	global_load_dwordx4 v[166:169], v[222:223], off offset:512
	global_load_dwordx4 v[172:175], v[224:225], off offset:512
	global_load_dwordx4 v[176:179], v[226:227], off offset:512
	global_load_dwordx4 v[180:183], v[232:233], off offset:512
	v_cmp_le_u32_e64 s[44:45], s42, v206
	v_cmp_le_u32_e64 s[46:47], s42, v207
	v_cmp_le_u32_e64 s[48:49], s42, v208
	v_cmp_le_u32_e64 s[50:51], s42, v209
	v_cmp_le_u32_e64 s[52:53], s42, v216
	v_cmp_le_u32_e32 vcc, s42, v217
	s_waitcnt vmcnt(14)
	v_pk_mul_f32 v[184:185], v[184:185], 0.5 op_sel_hi:[1,0]
	v_pk_mul_f32 v[186:187], v[186:187], 0.5 op_sel_hi:[1,0]
	v_pk_mul_f32 v[188:189], v[188:189], 0.5 op_sel_hi:[1,0]
	v_pk_mul_f32 v[190:191], v[190:191], 0.5 op_sel_hi:[1,0]
	v_cndmask_b32_e64 v242, v184, v188, s[44:45]
	v_cndmask_b32_e64 v243, v185, v189, s[44:45]
	v_cndmask_b32_e64 v244, v186, v190, s[44:45]
	v_cndmask_b32_e64 v245, v187, v191, s[44:45]
	v_pk_fma_f32 v[92:93], v[92:93], v[242:243], v[98:99]
	v_pk_fma_f32 v[94:95], v[94:95], v[244:245], v[100:101]
	v_cndmask_b32_e64 v242, v184, v188, s[46:47]
	v_cndmask_b32_e64 v243, v185, v189, s[46:47]
	v_cndmask_b32_e64 v244, v186, v190, s[46:47]
	v_cndmask_b32_e64 v245, v187, v191, s[46:47]
	v_pk_fma_f32 v[88:89], v[88:89], v[242:243], v[102:103]
	v_pk_fma_f32 v[90:91], v[90:91], v[244:245], v[104:105]
	v_cndmask_b32_e64 v242, v184, v188, s[48:49]
	v_cndmask_b32_e64 v243, v185, v189, s[48:49]
	v_cndmask_b32_e64 v244, v186, v190, s[48:49]
	v_cndmask_b32_e64 v245, v187, v191, s[48:49]
	v_pk_fma_f32 v[84:85], v[84:85], v[242:243], v[106:107]
	v_pk_fma_f32 v[86:87], v[86:87], v[244:245], v[108:109]
	v_cndmask_b32_e64 v242, v184, v188, s[50:51]
	v_cndmask_b32_e64 v243, v185, v189, s[50:51]
	v_cndmask_b32_e64 v244, v186, v190, s[50:51]
	v_cndmask_b32_e64 v245, v187, v191, s[50:51]
	v_pk_fma_f32 v[76:77], v[76:77], v[242:243], v[110:111]
	v_pk_fma_f32 v[78:79], v[78:79], v[244:245], v[112:113]
	v_cndmask_b32_e64 v242, v184, v188, s[52:53]
	v_cndmask_b32_e64 v243, v185, v189, s[52:53]
	v_cndmask_b32_e64 v244, v186, v190, s[52:53]
	v_cndmask_b32_e64 v245, v187, v191, s[52:53]
	v_pk_fma_f32 v[72:73], v[72:73], v[242:243], v[114:115]
	v_pk_fma_f32 v[74:75], v[74:75], v[244:245], v[116:117]
	v_cndmask_b32_e32 v242, v184, v188, vcc
	v_cndmask_b32_e32 v243, v185, v189, vcc
	v_cndmask_b32_e32 v244, v186, v190, vcc
	v_cndmask_b32_e32 v245, v187, v191, vcc
	v_pk_fma_f32 v[64:65], v[64:65], v[242:243], v[118:119]
	v_pk_fma_f32 v[66:67], v[66:67], v[244:245], v[120:121]
	global_load_dwordx4 v[98:101], v[218:219], off offset:576
	global_load_dwordx4 v[102:105], v[220:221], off offset:576
	global_load_dwordx4 v[106:109], v[222:223], off offset:576
	global_load_dwordx4 v[110:113], v[224:225], off offset:576
	global_load_dwordx4 v[114:117], v[226:227], off offset:576
	global_load_dwordx4 v[118:121], v[232:233], off offset:576
	global_load_dwordx4 v[184:187], v96, s[0:1] offset:512
	global_load_dwordx4 v[188:191], v96, s[30:31] offset:512
	global_load_dwordx4 v[234:237], v96, s[0:1] offset:576
	global_load_dwordx4 v[238:241], v96, s[30:31] offset:576
	s_waitcnt vmcnt(16)
	v_pk_mul_f32 v[192:193], v[192:193], 0.5 op_sel_hi:[1,0]
	v_pk_mul_f32 v[194:195], v[194:195], 0.5 op_sel_hi:[1,0]
	v_pk_mul_f32 v[196:197], v[196:197], 0.5 op_sel_hi:[1,0]
	v_pk_mul_f32 v[198:199], v[198:199], 0.5 op_sel_hi:[1,0]
	v_cndmask_b32_e64 v242, v192, v196, s[44:45]
	v_cndmask_b32_e64 v243, v193, v197, s[44:45]
	v_cndmask_b32_e64 v244, v194, v198, s[44:45]
	v_cndmask_b32_e64 v245, v195, v199, s[44:45]
	v_pk_fma_f32 v[80:81], v[80:81], v[242:243], v[122:123]
	v_pk_fma_f32 v[82:83], v[82:83], v[244:245], v[124:125]
	v_cndmask_b32_e64 v242, v192, v196, s[46:47]
	v_cndmask_b32_e64 v243, v193, v197, s[46:47]
	v_cndmask_b32_e64 v244, v194, v198, s[46:47]
	v_cndmask_b32_e64 v245, v195, v199, s[46:47]
	v_pk_fma_f32 v[68:69], v[68:69], v[242:243], v[126:127]
	v_pk_fma_f32 v[70:71], v[70:71], v[244:245], v[128:129]
	v_cndmask_b32_e64 v242, v192, v196, s[48:49]
	v_cndmask_b32_e64 v243, v193, v197, s[48:49]
	v_cndmask_b32_e64 v244, v194, v198, s[48:49]
	v_cndmask_b32_e64 v245, v195, v199, s[48:49]
	v_pk_fma_f32 v[60:61], v[60:61], v[242:243], v[130:131]
	v_pk_fma_f32 v[62:63], v[62:63], v[244:245], v[132:133]
	v_cndmask_b32_e64 v242, v192, v196, s[50:51]
	v_cndmask_b32_e64 v243, v193, v197, s[50:51]
	v_cndmask_b32_e64 v244, v194, v198, s[50:51]
	v_cndmask_b32_e64 v245, v195, v199, s[50:51]
	v_pk_fma_f32 v[56:57], v[56:57], v[242:243], v[134:135]
	v_pk_fma_f32 v[58:59], v[58:59], v[244:245], v[136:137]
	v_cndmask_b32_e64 v242, v192, v196, s[52:53]
	v_cndmask_b32_e64 v243, v193, v197, s[52:53]
	v_cndmask_b32_e64 v244, v194, v198, s[52:53]
	v_cndmask_b32_e64 v245, v195, v199, s[52:53]
	v_pk_fma_f32 v[52:53], v[52:53], v[242:243], v[150:151]
	v_pk_fma_f32 v[54:55], v[54:55], v[244:245], v[152:153]
	v_cndmask_b32_e32 v242, v192, v196, vcc
	v_cndmask_b32_e32 v243, v193, v197, vcc
	v_cndmask_b32_e32 v244, v194, v198, vcc
	v_cndmask_b32_e32 v245, v195, v199, vcc
	v_pk_fma_f32 v[44:45], v[44:45], v[242:243], v[154:155]
	v_pk_fma_f32 v[46:47], v[46:47], v[244:245], v[156:157]
	s_waitcnt vmcnt(0)
	v_pk_mul_f32 v[184:185], v[184:185], 0.5 op_sel_hi:[1,0]
	v_pk_mul_f32 v[186:187], v[186:187], 0.5 op_sel_hi:[1,0]
	v_pk_mul_f32 v[188:189], v[188:189], 0.5 op_sel_hi:[1,0]
	v_pk_mul_f32 v[190:191], v[190:191], 0.5 op_sel_hi:[1,0]
	v_cndmask_b32_e64 v242, v184, v188, s[44:45]
	v_cndmask_b32_e64 v243, v185, v189, s[44:45]
	v_cndmask_b32_e64 v244, v186, v190, s[44:45]
	v_cndmask_b32_e64 v245, v187, v191, s[44:45]
	v_pk_fma_f32 v[48:49], v[48:49], v[242:243], v[158:159]
	v_pk_fma_f32 v[50:51], v[50:51], v[244:245], v[160:161]
	v_cndmask_b32_e64 v242, v184, v188, s[46:47]
	v_cndmask_b32_e64 v243, v185, v189, s[46:47]
	v_cndmask_b32_e64 v244, v186, v190, s[46:47]
	v_cndmask_b32_e64 v245, v187, v191, s[46:47]
	v_pk_fma_f32 v[40:41], v[40:41], v[242:243], v[162:163]
	v_pk_fma_f32 v[42:43], v[42:43], v[244:245], v[164:165]
	v_cndmask_b32_e64 v242, v184, v188, s[48:49]
	v_cndmask_b32_e64 v243, v185, v189, s[48:49]
	v_cndmask_b32_e64 v244, v186, v190, s[48:49]
	v_cndmask_b32_e64 v245, v187, v191, s[48:49]
	v_pk_fma_f32 v[36:37], v[36:37], v[242:243], v[166:167]
	v_pk_fma_f32 v[38:39], v[38:39], v[244:245], v[168:169]
	v_cndmask_b32_e64 v242, v184, v188, s[50:51]
	v_cndmask_b32_e64 v243, v185, v189, s[50:51]
	v_cndmask_b32_e64 v244, v186, v190, s[50:51]
	v_cndmask_b32_e64 v245, v187, v191, s[50:51]
	v_pk_fma_f32 v[32:33], v[32:33], v[242:243], v[172:173]
	v_pk_fma_f32 v[34:35], v[34:35], v[244:245], v[174:175]
	v_cndmask_b32_e64 v242, v184, v188, s[52:53]
	v_cndmask_b32_e64 v243, v185, v189, s[52:53]
	v_cndmask_b32_e64 v244, v186, v190, s[52:53]
	v_cndmask_b32_e64 v245, v187, v191, s[52:53]
	v_pk_fma_f32 v[24:25], v[24:25], v[242:243], v[176:177]
	v_pk_fma_f32 v[26:27], v[26:27], v[244:245], v[178:179]
	v_cndmask_b32_e32 v242, v184, v188, vcc
	v_cndmask_b32_e32 v243, v185, v189, vcc
	v_cndmask_b32_e32 v244, v186, v190, vcc
	v_cndmask_b32_e32 v245, v187, v191, vcc
	v_pk_fma_f32 v[16:17], v[16:17], v[242:243], v[180:181]
	v_pk_fma_f32 v[18:19], v[18:19], v[244:245], v[182:183]
	v_pk_mul_f32 v[234:235], v[234:235], 0.5 op_sel_hi:[1,0]
	v_pk_mul_f32 v[236:237], v[236:237], 0.5 op_sel_hi:[1,0]
	v_pk_mul_f32 v[238:239], v[238:239], 0.5 op_sel_hi:[1,0]
	v_pk_mul_f32 v[240:241], v[240:241], 0.5 op_sel_hi:[1,0]
	v_cndmask_b32_e64 v242, v234, v238, s[44:45]
	v_cndmask_b32_e64 v243, v235, v239, s[44:45]
	v_cndmask_b32_e64 v244, v236, v240, s[44:45]
	v_cndmask_b32_e64 v245, v237, v241, s[44:45]
	v_pk_fma_f32 v[28:29], v[28:29], v[242:243], v[98:99]
	v_pk_fma_f32 v[30:31], v[30:31], v[244:245], v[100:101]
	v_cndmask_b32_e64 v242, v234, v238, s[46:47]
	v_cndmask_b32_e64 v243, v235, v239, s[46:47]
	v_cndmask_b32_e64 v244, v236, v240, s[46:47]
	v_cndmask_b32_e64 v245, v237, v241, s[46:47]
	v_pk_fma_f32 v[20:21], v[20:21], v[242:243], v[102:103]
	v_pk_fma_f32 v[22:23], v[22:23], v[244:245], v[104:105]
	v_cndmask_b32_e64 v242, v234, v238, s[48:49]
	v_cndmask_b32_e64 v243, v235, v239, s[48:49]
	v_cndmask_b32_e64 v244, v236, v240, s[48:49]
	v_cndmask_b32_e64 v245, v237, v241, s[48:49]
	v_pk_fma_f32 v[12:13], v[12:13], v[242:243], v[106:107]
	v_pk_fma_f32 v[14:15], v[14:15], v[244:245], v[108:109]
	v_cndmask_b32_e64 v242, v234, v238, s[50:51]
	v_cndmask_b32_e64 v243, v235, v239, s[50:51]
	v_cndmask_b32_e64 v244, v236, v240, s[50:51]
	v_cndmask_b32_e64 v245, v237, v241, s[50:51]
	v_pk_fma_f32 v[8:9], v[8:9], v[242:243], v[110:111]
	v_pk_fma_f32 v[10:11], v[10:11], v[244:245], v[112:113]
	v_cndmask_b32_e64 v242, v234, v238, s[52:53]
	v_cndmask_b32_e64 v243, v235, v239, s[52:53]
	v_cndmask_b32_e64 v244, v236, v240, s[52:53]
	v_cndmask_b32_e64 v245, v237, v241, s[52:53]
	v_pk_fma_f32 v[4:5], v[4:5], v[242:243], v[114:115]
	v_pk_fma_f32 v[6:7], v[6:7], v[244:245], v[116:117]
	v_cndmask_b32_e32 v242, v234, v238, vcc
	v_cndmask_b32_e32 v243, v235, v239, vcc
	v_cndmask_b32_e32 v244, v236, v240, vcc
	v_cndmask_b32_e32 v245, v237, v241, vcc
	v_pk_fma_f32 v[0:1], v[0:1], v[242:243], v[118:119]
	v_pk_fma_f32 v[2:3], v[2:3], v[244:245], v[120:121]
	global_store_dwordx4 v206, v[92:95], s[90:91] offset:0
	global_store_dwordx4 v207, v[88:91], s[90:91] offset:0
	global_store_dwordx4 v208, v[84:87], s[90:91] offset:0
	global_store_dwordx4 v209, v[76:79], s[90:91] offset:0
	global_store_dwordx4 v216, v[72:75], s[90:91] offset:0
	global_store_dwordx4 v217, v[64:67], s[90:91] offset:0
	global_store_dwordx4 v206, v[80:83], s[90:91] offset:64
	global_store_dwordx4 v207, v[68:71], s[90:91] offset:64
	global_store_dwordx4 v208, v[60:63], s[90:91] offset:64
	global_store_dwordx4 v209, v[56:59], s[90:91] offset:64
	global_store_dwordx4 v216, v[52:55], s[90:91] offset:64
	global_store_dwordx4 v217, v[44:47], s[90:91] offset:64
	global_store_dwordx4 v206, v[48:51], s[90:91] offset:512
	global_store_dwordx4 v207, v[40:43], s[90:91] offset:512
	global_store_dwordx4 v208, v[36:39], s[90:91] offset:512
	global_store_dwordx4 v209, v[32:35], s[90:91] offset:512
	global_store_dwordx4 v216, v[24:27], s[90:91] offset:512
	global_store_dwordx4 v217, v[16:19], s[90:91] offset:512
	global_store_dwordx4 v206, v[28:31], s[90:91] offset:576
	global_store_dwordx4 v207, v[20:23], s[90:91] offset:576
	global_store_dwordx4 v208, v[12:15], s[90:91] offset:576
	global_store_dwordx4 v209, v[8:11], s[90:91] offset:576
	global_store_dwordx4 v216, v[4:7], s[90:91] offset:576
	global_store_dwordx4 v217, v[0:3], s[90:91] offset:576
	s_branch .LBB0_470

.LBB0_527:
	v_readlane_b32 s80, v255, 42
	v_readlane_b32 s84, v255, 44
	v_readlane_b32 s81, v255, 43
	v_readlane_b32 s85, v255, 45
	v_readlane_b32 s77, v255, 46
	v_readlane_b32 s76, v255, 47
	s_barrier
	s_cmp_lt_u32 s34, 64
	s_cbranch_scc1 .Lp0t_done_q1
	v_readlane_b32 s0, v255, 48
	s_cmp_eq_u32 s0, 2
	s_cbranch_scc0 .Lp0t_n0_q1
	s_sub_i32 s32, s34, 64
	s_addk_i32 s32, 0x450
	s_movk_i32 s69, 0x65f
	s_cmp_gt_i32 s32, s69
	s_cbranch_scc1 .Lp0t_done_q1
	s_movk_i32 s68, 0xc0
	s_mov_b32 s70, 0
	s_mov_b32 s71, 0
	v_mov_b32_e32 v0, v204
	s_branch .Lp0_reenter
.Lp0t_n0_q1:
	s_cmp_eq_u32 s0, 14
	s_cbranch_scc0 .Lp0t_n1_q1
	s_sub_i32 s32, s34, 64
	s_addk_i32 s32, 0x870
	s_movk_i32 s69, 0xa7f
	s_cmp_gt_i32 s32, s69
	s_cbranch_scc1 .Lp0t_done_q1
	s_movk_i32 s68, 0xc0
	s_mov_b32 s70, 0
	s_mov_b32 s71, 0
	v_mov_b32_e32 v0, v204
	s_branch .Lp0_reenter

.LBB0_572:
	s_or_b64 exec, exec, s[0:1]
	v_readlane_b32 s0, v252, 44
	v_readlane_b32 s1, v252, 45
	s_andn2_b64 vcc, exec, s[0:1]
	s_waitcnt vmcnt(0) lgkmcnt(0)
	s_barrier
	s_cbranch_vccnz .LBB0_622
	s_mov_b32 s32, s34
	s_mov_b32 s68, s54
	s_movk_i32 s69, 0x10bf
	s_movk_i32 s70, 0x450
	s_movk_i32 s71, 0xa80
.Lp0_reenter:
	v_lshlrev_b32_e32 v1, 3, v0
	v_and_b32_e32 v2, 0x1f8, v1
	v_readlane_b32 s0, v253, 63
	v_lshlrev_b32_e32 v96, 1, v2
	v_readlane_b32 s1, v254, 0
	v_and_b32_e32 v65, 56, v1
	v_readlane_b32 s4, v254, 58
	v_lshl_add_u64 v[42:43], s[0:1], 0, v[96:97]
	v_readlane_b32 s0, v251, 30
	v_lshlrev_b32_e32 v96, 1, v65
	v_readlane_b32 s1, v251, 31
	v_bfe_u32 v51, v1, 6, 3
	v_lshlrev_b32_e32 v1, 6, v0
	v_lshl_add_u64 v[44:45], s[0:1], 0, v[96:97]
	v_readlane_b32 s0, v251, 51
	v_readlane_b32 s1, v251, 52
	v_and_b32_e32 v48, 31, v0
	v_ashrrev_i32_e32 v50, 5, v0
	v_lshl_add_u64 v[46:47], s[0:1], 0, v[96:97]
	s_movk_i32 s0, 0x120
	v_cmp_gt_i32_e64 s[40:41], s0, v0
	s_movk_i32 s0, 0x480
	v_readlane_b32 s8, v254, 62
	v_readlane_b32 s9, v254, 63
	v_add_u32_e32 v49, 0xffe08000, v0
	v_add_u32_e32 v71, 0xffe28000, v0
	v_bfe_u32 v77, v0, 3, 2
	v_add_u32_e32 v79, 0xffe68000, v0
	v_bfe_u32 v81, v0, 4, 2
	v_and_b32_e32 v83, 0x200, v1
	v_lshlrev_b32_e32 v2, 6, v50
	v_lshl_add_u32 v3, v48, 2, 0
	v_mul_lo_u32 v4, v50, s0
	v_lshlrev_b32_e32 v5, 7, v50
	v_mov_b64_e32 v[0:1], s[8:9]
	s_mov_b32 s0, 0x9000
	v_lshl_add_u32 v88, v50, 8, 0
	v_mad_i64_i32 v[52:53], s[0:1], v2, s0, v[0:1]
	v_add_u32_e32 v89, v3, v4
	v_add_u32_e32 v90, v3, v5
	s_mov_b32 s3, s32
	v_readlane_b32 s5, v254, 59
	v_readlane_b32 s6, v254, 60
	v_readlane_b32 s7, v254, 61
	v_readlane_b32 s10, v255, 0
	v_readlane_b32 s11, v255, 1
	v_readlane_b32 s12, v255, 2
	v_readlane_b32 s13, v255, 3
	v_readlane_b32 s14, v255, 4
	v_readlane_b32 s15, v255, 5
	v_readlane_b32 s16, v255, 6
	v_readlane_b32 s17, v255, 7
	v_readlane_b32 s18, v255, 8
	v_readlane_b32 s19, v255, 9
	s_branch .LBB0_576

.LBB0_575:
	s_add_i32 s3, s3, s68
	s_cmp_gt_i32 s3, s69
	s_cbranch_scc1 .LBB0_622
.LBB0_576:
	s_cmp_ge_u32 s3, s70
	s_cbranch_scc0 .Lp0_go
	s_cmp_lt_u32 s3, s71
	s_cbranch_scc1 .LBB0_575
